# GEMM main loops: hipcc per-cluster s_setprio flips deleted, one static s_setprio 1 for waves 4-7 before each loop, reset at loop exit
# speedup vs baseline: 1.0089x; 1.0041x over previous
.LBB0_205:
	s_ashr_i32 s43, s42, 31
	s_lshl_b64 s[6:7], s[42:43], 19
	v_readlane_b32 s14, v252, 47
	v_readlane_b32 s15, v252, 48
	s_add_u32 s44, s14, s6
	s_addc_u32 s45, s15, s7
	s_and_b64 s[6:7], s[38:39], exec
	s_cselect_b32 s43, s45, s49
	s_cselect_b32 s73, s44, s48
	s_ashr_i32 s41, s40, 31
	s_lshl_b64 s[6:7], s[40:41], 19
	s_add_u32 s46, s16, s6
	s_addc_u32 s47, s17, s7
	s_and_b64 s[6:7], s[38:39], exec
	s_cselect_b32 s75, s47, s13
	s_cselect_b32 s88, s46, s12
	s_lshl_b32 s41, s1, 8
	s_add_u32 s6, s12, 0x100
	v_lshl_add_u32 v169, s10, 8, v3
	s_movk_i32 s0, 0x1300
	s_addc_u32 s7, s13, 0
	v_mul_lo_u32 v170, v169, s0
	s_add_u32 s0, s48, 0x40080
	s_addc_u32 s1, s49, 0
	v_mov_b32_e32 v4, 0
	v_add_u32_e32 v171, s41, v166
	v_add_u32_e32 v168, 0x13000, v170
	v_lshl_add_u64 v[160:161], s[0:1], 0, v[146:147]
	v_lshl_add_u64 v[162:163], s[0:1], 0, v[158:159]
	s_mov_b32 s0, -2
	s_mov_b64 s[50:51], 0
	s_waitcnt lgkmcnt(0)
	s_waitcnt lgkmcnt(0)
	v_mov_b64_e32 v[4:5], 0
	v_mov_b64_e32 v[6:7], 0
	v_mov_b64_e32 v[8:9], 0
	v_mov_b64_e32 v[10:11], 0
	v_mov_b64_e32 v[12:13], 0
	v_mov_b64_e32 v[14:15], 0
	v_mov_b64_e32 v[16:17], 0
	v_mov_b64_e32 v[18:19], 0
	v_mov_b64_e32 v[20:21], 0
	v_mov_b64_e32 v[22:23], 0
	v_mov_b64_e32 v[24:25], 0
	v_mov_b64_e32 v[26:27], 0
	v_mov_b64_e32 v[28:29], 0
	v_mov_b64_e32 v[30:31], 0
	v_mov_b64_e32 v[32:33], 0
	v_mov_b64_e32 v[34:35], 0
	v_mov_b64_e32 v[36:37], 0
	v_mov_b64_e32 v[38:39], 0
	v_mov_b64_e32 v[40:41], 0
	v_mov_b64_e32 v[42:43], 0
	v_mov_b64_e32 v[44:45], 0
	v_mov_b64_e32 v[46:47], 0
	v_mov_b64_e32 v[48:49], 0
	v_mov_b64_e32 v[50:51], 0
	v_mov_b64_e32 v[52:53], 0
	v_mov_b64_e32 v[54:55], 0
	v_mov_b64_e32 v[56:57], 0
	v_mov_b64_e32 v[58:59], 0
	v_mov_b64_e32 v[60:61], 0
	v_mov_b64_e32 v[62:63], 0
	v_mov_b64_e32 v[64:65], 0
	v_mov_b64_e32 v[66:67], 0
	v_mov_b64_e32 v[68:69], 0
	v_mov_b64_e32 v[70:71], 0
	v_mov_b64_e32 v[72:73], 0
	v_mov_b64_e32 v[74:75], 0
	v_mov_b64_e32 v[76:77], 0
	v_mov_b64_e32 v[78:79], 0
	v_mov_b64_e32 v[80:81], 0
	v_mov_b64_e32 v[82:83], 0
	v_mov_b64_e32 v[84:85], 0
	v_mov_b64_e32 v[86:87], 0
	v_mov_b64_e32 v[88:89], 0
	v_mov_b64_e32 v[90:91], 0
	v_mov_b64_e32 v[92:93], 0
	v_mov_b64_e32 v[94:95], 0
	v_mov_b64_e32 v[96:97], 0
	v_mov_b64_e32 v[98:99], 0
	v_mov_b64_e32 v[100:101], 0
	v_mov_b64_e32 v[102:103], 0
	v_mov_b64_e32 v[104:105], 0
	v_mov_b64_e32 v[106:107], 0
	v_mov_b64_e32 v[108:109], 0
	v_mov_b64_e32 v[110:111], 0
	v_mov_b64_e32 v[112:113], 0
	v_mov_b64_e32 v[114:115], 0
	v_mov_b64_e32 v[116:117], 0
	v_mov_b64_e32 v[118:119], 0
	v_mov_b64_e32 v[120:121], 0
	v_mov_b64_e32 v[122:123], 0
	v_mov_b64_e32 v[124:125], 0
	v_mov_b64_e32 v[126:127], 0
	v_mov_b64_e32 v[128:129], 0
	v_mov_b64_e32 v[130:131], 0
	v_readfirstlane_b32 s35, v176
	s_nop 3
	s_lshr_b32 s35, s35, 6
	s_cmp_ge_u32 s35, 4
	s_cbranch_scc0 .Lsp_done_0
	s_setprio 1

.LBB0_206:
	s_add_u32 s1, s48, s50
	s_addc_u32 s10, s49, s51
	s_add_u32 s1, s1, 0x100
	s_addc_u32 s10, s10, 0
	s_add_u32 s14, s6, s50
	s_addc_u32 s11, s7, s51
	s_add_i32 s15, 0, 0x10000
	s_cmpk_eq_i32 s50, 0x700
	s_cselect_b32 s13, s43, s10
	s_cselect_b32 s12, s73, s1
	v_add_u32_e32 v152, s15, v164
	s_cselect_b32 s11, s75, s11
	s_cselect_b32 s10, s88, s14
	s_add_i32 s1, 0, 0x14000
	ds_read_b128 v[132:135], v152
	ds_read_b128 v[136:139], v152 offset:1024
	ds_read_b128 v[172:175], v152 offset:2048
	ds_read_b128 v[190:193], v152 offset:3072
	v_add_u32_e32 v152, s1, v164
	ds_read_b128 v[194:197], v152
	ds_read_b128 v[198:201], v152 offset:1024
	ds_read_b128 v[202:205], v152 offset:2048
	ds_read_b128 v[206:209], v152 offset:3072
	v_lshl_add_u64 v[152:153], v[162:163], 0, s[50:51]
	s_add_i32 m0, s52, 0xc000
	ds_read_b128 v[210:213], v167
	ds_read_b128 v[214:217], v167 offset:1024
	ds_read_b128 v[218:221], v167 offset:2048
	ds_read_b128 v[222:225], v167 offset:3072
	ds_read_b128 v[226:229], v167 offset:4096
	ds_read_b128 v[230:233], v167 offset:5120
	ds_read_b128 v[234:237], v167 offset:6144
	ds_read_b128 v[238:241], v167 offset:7168
	global_load_lds_dwordx4 v[152:153], off
	v_lshl_add_u64 v[152:153], v[160:161], 0, s[50:51]
	s_add_i32 m0, s52, 0xe000
	s_nop 0
	global_load_lds_dwordx4 v[152:153], off
	s_waitcnt vmcnt(8)
	s_waitcnt lgkmcnt(0)
	s_barrier
	s_waitcnt lgkmcnt(0)
	v_mfma_f32_16x16x32_bf16 v[128:131], v[132:135], v[210:213], v[128:131]
	v_mfma_f32_16x16x32_bf16 v[124:127], v[172:175], v[210:213], v[124:127]
	v_mfma_f32_16x16x32_bf16 v[112:115], v[132:135], v[218:221], v[112:115]
	v_mfma_f32_16x16x32_bf16 v[108:111], v[172:175], v[218:221], v[108:111]
	v_mfma_f32_16x16x32_bf16 v[96:99], v[132:135], v[226:229], v[96:99]
	v_mfma_f32_16x16x32_bf16 v[92:95], v[172:175], v[226:229], v[92:95]
	v_mfma_f32_16x16x32_bf16 v[80:83], v[132:135], v[234:237], v[80:83]
	v_mfma_f32_16x16x32_bf16 v[76:79], v[172:175], v[234:237], v[76:79]
	v_mfma_f32_16x16x32_bf16 v[128:131], v[136:139], v[214:217], v[128:131]
	v_mfma_f32_16x16x32_bf16 v[124:127], v[190:193], v[214:217], v[124:127]
	v_mfma_f32_16x16x32_bf16 v[112:115], v[136:139], v[222:225], v[112:115]
	v_mfma_f32_16x16x32_bf16 v[108:111], v[190:193], v[222:225], v[108:111]
	v_mfma_f32_16x16x32_bf16 v[96:99], v[136:139], v[230:233], v[96:99]
	v_mfma_f32_16x16x32_bf16 v[92:95], v[190:193], v[230:233], v[92:95]
	v_mfma_f32_16x16x32_bf16 v[80:83], v[136:139], v[238:241], v[80:83]
	v_mfma_f32_16x16x32_bf16 v[76:79], v[190:193], v[238:241], v[76:79]
	v_mfma_f32_16x16x32_bf16 v[120:123], v[194:197], v[210:213], v[120:123]
	v_mfma_f32_16x16x32_bf16 v[116:119], v[202:205], v[210:213], v[116:119]
	v_mfma_f32_16x16x32_bf16 v[104:107], v[194:197], v[218:221], v[104:107]
	v_mfma_f32_16x16x32_bf16 v[100:103], v[202:205], v[218:221], v[100:103]
	v_mfma_f32_16x16x32_bf16 v[88:91], v[194:197], v[226:229], v[88:91]
	v_mfma_f32_16x16x32_bf16 v[84:87], v[202:205], v[226:229], v[84:87]
	v_mfma_f32_16x16x32_bf16 v[72:75], v[194:197], v[234:237], v[72:75]
	v_mfma_f32_16x16x32_bf16 v[68:71], v[202:205], v[234:237], v[68:71]
	v_mfma_f32_16x16x32_bf16 v[120:123], v[198:201], v[214:217], v[120:123]
	v_mfma_f32_16x16x32_bf16 v[116:119], v[206:209], v[214:217], v[116:119]
	v_mfma_f32_16x16x32_bf16 v[104:107], v[198:201], v[222:225], v[104:107]
	v_mfma_f32_16x16x32_bf16 v[100:103], v[206:209], v[222:225], v[100:103]
	v_mfma_f32_16x16x32_bf16 v[88:91], v[198:201], v[230:233], v[88:91]
	v_mfma_f32_16x16x32_bf16 v[84:87], v[206:209], v[230:233], v[84:87]
	v_mfma_f32_16x16x32_bf16 v[72:75], v[198:201], v[238:241], v[72:75]
	v_mfma_f32_16x16x32_bf16 v[68:71], v[206:209], v[238:241], v[68:71]
	s_barrier
	s_add_i32 s14, s15, s19
	v_lshl_add_u64 v[152:153], s[10:11], 0, v[140:141]
	s_mov_b32 m0, s14
	ds_read_b128 v[210:213], v167 offset:16384
	ds_read_b128 v[214:217], v167 offset:17408
	ds_read_b128 v[218:221], v167 offset:18432
	ds_read_b128 v[222:225], v167 offset:19456
	ds_read_b128 v[226:229], v167 offset:20480
	ds_read_b128 v[230:233], v167 offset:21504
	ds_read_b128 v[234:237], v167 offset:22528
	ds_read_b128 v[238:241], v167 offset:23552
	global_load_lds_dwordx4 v[152:153], off
	s_add_i32 m0, s14, 0x2000
	s_add_u32 s14, s10, 0x40000
	v_lshl_add_u64 v[242:243], s[10:11], 0, v[144:145]
	s_addc_u32 s15, s11, 0
	s_add_i32 s1, s1, s19
	global_load_lds_dwordx4 v[242:243], off
	v_lshl_add_u64 v[244:245], s[14:15], 0, v[140:141]
	s_mov_b32 m0, s1
	v_lshl_add_u64 v[246:247], s[12:13], 0, v[142:143]
	global_load_lds_dwordx4 v[244:245], off
	v_lshl_add_u64 v[244:245], s[14:15], 0, v[144:145]
	s_add_i32 m0, s1, 0x2000
	s_nop 0
	global_load_lds_dwordx4 v[244:245], off
	v_lshl_add_u64 v[244:245], s[12:13], 0, v[0:1]
	s_mov_b32 m0, s52
	s_nop 0
	global_load_lds_dwordx4 v[244:245], off
	s_mov_b32 m0, s53
	s_nop 0
	global_load_lds_dwordx4 v[246:247], off
	s_waitcnt vmcnt(8)
	s_waitcnt lgkmcnt(0)
	s_barrier
	s_waitcnt lgkmcnt(0)
	v_mfma_f32_16x16x32_bf16 v[64:67], v[132:135], v[210:213], v[64:67]
	v_mfma_f32_16x16x32_bf16 v[60:63], v[172:175], v[210:213], v[60:63]
	v_mfma_f32_16x16x32_bf16 v[48:51], v[132:135], v[218:221], v[48:51]
	v_mfma_f32_16x16x32_bf16 v[44:47], v[172:175], v[218:221], v[44:47]
	v_mfma_f32_16x16x32_bf16 v[32:35], v[132:135], v[226:229], v[32:35]
	v_mfma_f32_16x16x32_bf16 v[28:31], v[172:175], v[226:229], v[28:31]
	v_mfma_f32_16x16x32_bf16 v[16:19], v[132:135], v[234:237], v[16:19]
	v_mfma_f32_16x16x32_bf16 v[12:15], v[172:175], v[234:237], v[12:15]
	v_mfma_f32_16x16x32_bf16 v[64:67], v[136:139], v[214:217], v[64:67]
	v_mfma_f32_16x16x32_bf16 v[60:63], v[190:193], v[214:217], v[60:63]
	v_mfma_f32_16x16x32_bf16 v[48:51], v[136:139], v[222:225], v[48:51]
	v_mfma_f32_16x16x32_bf16 v[44:47], v[190:193], v[222:225], v[44:47]
	v_mfma_f32_16x16x32_bf16 v[32:35], v[136:139], v[230:233], v[32:35]
	v_mfma_f32_16x16x32_bf16 v[28:31], v[190:193], v[230:233], v[28:31]
	v_mfma_f32_16x16x32_bf16 v[16:19], v[136:139], v[238:241], v[16:19]
	v_mfma_f32_16x16x32_bf16 v[12:15], v[190:193], v[238:241], v[12:15]
	v_mfma_f32_16x16x32_bf16 v[56:59], v[194:197], v[210:213], v[56:59]
	v_mfma_f32_16x16x32_bf16 v[52:55], v[202:205], v[210:213], v[52:55]
	v_mfma_f32_16x16x32_bf16 v[40:43], v[194:197], v[218:221], v[40:43]
	v_mfma_f32_16x16x32_bf16 v[36:39], v[202:205], v[218:221], v[36:39]
	v_mfma_f32_16x16x32_bf16 v[24:27], v[194:197], v[226:229], v[24:27]
	v_mfma_f32_16x16x32_bf16 v[20:23], v[202:205], v[226:229], v[20:23]
	v_mfma_f32_16x16x32_bf16 v[8:11], v[194:197], v[234:237], v[8:11]
	v_mfma_f32_16x16x32_bf16 v[4:7], v[202:205], v[234:237], v[4:7]
	v_mfma_f32_16x16x32_bf16 v[56:59], v[198:201], v[214:217], v[56:59]
	v_mfma_f32_16x16x32_bf16 v[52:55], v[206:209], v[214:217], v[52:55]
	v_mfma_f32_16x16x32_bf16 v[40:43], v[198:201], v[222:225], v[40:43]
	v_mfma_f32_16x16x32_bf16 v[36:39], v[206:209], v[222:225], v[36:39]
	v_mfma_f32_16x16x32_bf16 v[24:27], v[198:201], v[230:233], v[24:27]
	v_mfma_f32_16x16x32_bf16 v[20:23], v[206:209], v[230:233], v[20:23]
	v_mfma_f32_16x16x32_bf16 v[8:11], v[198:201], v[238:241], v[8:11]
	v_mfma_f32_16x16x32_bf16 v[4:7], v[206:209], v[238:241], v[4:7]
	s_barrier
	s_add_i32 s1, 0, 0x18000
	s_add_i32 s14, 0, 0x1c000
	v_add_u32_e32 v190, s1, v164
	v_add_u32_e32 v206, s14, v164
	ds_read_b128 v[132:135], v190
	ds_read_b128 v[136:139], v190 offset:1024
	ds_read_b128 v[172:175], v190 offset:2048
	ds_read_b128 v[190:193], v190 offset:3072
	ds_read_b128 v[194:197], v206
	ds_read_b128 v[198:201], v206 offset:1024
	ds_read_b128 v[202:205], v206 offset:2048
	ds_read_b128 v[206:209], v206 offset:3072
	s_add_u32 s12, s12, 0x40000
	s_addc_u32 s13, s13, 0
	s_mov_b32 m0, s54
	v_lshl_add_u64 v[248:249], s[12:13], 0, v[0:1]
	ds_read_b128 v[210:213], v167 offset:32768
	ds_read_b128 v[214:217], v167 offset:33792
	ds_read_b128 v[218:221], v167 offset:34816
	ds_read_b128 v[222:225], v167 offset:35840
	ds_read_b128 v[226:229], v167 offset:36864
	ds_read_b128 v[230:233], v167 offset:37888
	ds_read_b128 v[234:237], v167 offset:38912
	ds_read_b128 v[238:241], v167 offset:39936
	global_load_lds_dwordx4 v[248:249], off
	v_lshl_add_u64 v[248:249], s[12:13], 0, v[142:143]
	s_mov_b32 m0, s55
	s_nop 0
	global_load_lds_dwordx4 v[248:249], off
	s_waitcnt vmcnt(8)
	s_waitcnt lgkmcnt(0)
	s_barrier
	s_waitcnt lgkmcnt(0)
	v_mfma_f32_16x16x32_bf16 v[128:131], v[132:135], v[210:213], v[128:131]
	v_mfma_f32_16x16x32_bf16 v[124:127], v[172:175], v[210:213], v[124:127]
	v_mfma_f32_16x16x32_bf16 v[112:115], v[132:135], v[218:221], v[112:115]
	v_mfma_f32_16x16x32_bf16 v[108:111], v[172:175], v[218:221], v[108:111]
	v_mfma_f32_16x16x32_bf16 v[96:99], v[132:135], v[226:229], v[96:99]
	v_mfma_f32_16x16x32_bf16 v[92:95], v[172:175], v[226:229], v[92:95]
	v_mfma_f32_16x16x32_bf16 v[80:83], v[132:135], v[234:237], v[80:83]
	v_mfma_f32_16x16x32_bf16 v[76:79], v[172:175], v[234:237], v[76:79]
	v_mfma_f32_16x16x32_bf16 v[128:131], v[136:139], v[214:217], v[128:131]
	v_mfma_f32_16x16x32_bf16 v[124:127], v[190:193], v[214:217], v[124:127]
	v_mfma_f32_16x16x32_bf16 v[112:115], v[136:139], v[222:225], v[112:115]
	v_mfma_f32_16x16x32_bf16 v[108:111], v[190:193], v[222:225], v[108:111]
	v_mfma_f32_16x16x32_bf16 v[96:99], v[136:139], v[230:233], v[96:99]
	v_mfma_f32_16x16x32_bf16 v[92:95], v[190:193], v[230:233], v[92:95]
	v_mfma_f32_16x16x32_bf16 v[80:83], v[136:139], v[238:241], v[80:83]
	v_mfma_f32_16x16x32_bf16 v[76:79], v[190:193], v[238:241], v[76:79]
	v_mfma_f32_16x16x32_bf16 v[120:123], v[194:197], v[210:213], v[120:123]
	v_mfma_f32_16x16x32_bf16 v[116:119], v[202:205], v[210:213], v[116:119]
	v_mfma_f32_16x16x32_bf16 v[104:107], v[194:197], v[218:221], v[104:107]
	v_mfma_f32_16x16x32_bf16 v[100:103], v[202:205], v[218:221], v[100:103]
	v_mfma_f32_16x16x32_bf16 v[88:91], v[194:197], v[226:229], v[88:91]
	v_mfma_f32_16x16x32_bf16 v[84:87], v[202:205], v[226:229], v[84:87]
	v_mfma_f32_16x16x32_bf16 v[72:75], v[194:197], v[234:237], v[72:75]
	v_mfma_f32_16x16x32_bf16 v[68:71], v[202:205], v[234:237], v[68:71]
	v_mfma_f32_16x16x32_bf16 v[120:123], v[198:201], v[214:217], v[120:123]
	v_mfma_f32_16x16x32_bf16 v[116:119], v[206:209], v[214:217], v[116:119]
	v_mfma_f32_16x16x32_bf16 v[104:107], v[198:201], v[222:225], v[104:107]
	v_mfma_f32_16x16x32_bf16 v[100:103], v[206:209], v[222:225], v[100:103]
	v_mfma_f32_16x16x32_bf16 v[88:91], v[198:201], v[230:233], v[88:91]
	v_mfma_f32_16x16x32_bf16 v[84:87], v[206:209], v[230:233], v[84:87]
	v_mfma_f32_16x16x32_bf16 v[72:75], v[198:201], v[238:241], v[72:75]
	v_mfma_f32_16x16x32_bf16 v[68:71], v[206:209], v[238:241], v[68:71]
	s_barrier
	s_add_i32 s1, s1, s19
	v_lshl_add_u64 v[152:153], v[152:153], 0, s[84:85]
	s_mov_b32 m0, s1
	ds_read_b128 v[210:213], v167 offset:49152
	ds_read_b128 v[214:217], v167 offset:50176
	ds_read_b128 v[218:221], v167 offset:51200
	ds_read_b128 v[222:225], v167 offset:52224
	ds_read_b128 v[226:229], v167 offset:53248
	ds_read_b128 v[230:233], v167 offset:54272
	ds_read_b128 v[234:237], v167 offset:55296
	ds_read_b128 v[238:241], v167 offset:56320
	global_load_lds_dwordx4 v[152:153], off
	s_add_i32 m0, s1, 0x2000
	s_add_u32 s10, s10, 0x40080
	v_lshl_add_u64 v[152:153], v[242:243], 0, s[84:85]
	s_addc_u32 s11, s11, 0
	s_add_i32 s1, s14, s19
	global_load_lds_dwordx4 v[152:153], off
	v_lshl_add_u64 v[152:153], s[10:11], 0, v[140:141]
	s_mov_b32 m0, s1
	s_nop 0
	global_load_lds_dwordx4 v[152:153], off
	v_lshl_add_u64 v[152:153], s[10:11], 0, v[144:145]
	s_add_i32 m0, s1, 0x2000
	s_nop 0
	global_load_lds_dwordx4 v[152:153], off
	v_lshl_add_u64 v[152:153], v[244:245], 0, s[84:85]
	s_mov_b32 m0, s58
	s_nop 0
	global_load_lds_dwordx4 v[152:153], off
	v_lshl_add_u64 v[152:153], v[246:247], 0, s[84:85]
	s_mov_b32 m0, s59
	s_nop 0
	global_load_lds_dwordx4 v[152:153], off
	s_waitcnt vmcnt(8)
	s_waitcnt lgkmcnt(0)
	s_barrier
	s_waitcnt lgkmcnt(0)
	v_mfma_f32_16x16x32_bf16 v[64:67], v[132:135], v[210:213], v[64:67]
	v_mfma_f32_16x16x32_bf16 v[60:63], v[172:175], v[210:213], v[60:63]
	v_mfma_f32_16x16x32_bf16 v[48:51], v[132:135], v[218:221], v[48:51]
	v_mfma_f32_16x16x32_bf16 v[44:47], v[172:175], v[218:221], v[44:47]
	v_mfma_f32_16x16x32_bf16 v[32:35], v[132:135], v[226:229], v[32:35]
	v_mfma_f32_16x16x32_bf16 v[28:31], v[172:175], v[226:229], v[28:31]
	v_mfma_f32_16x16x32_bf16 v[16:19], v[132:135], v[234:237], v[16:19]
	v_mfma_f32_16x16x32_bf16 v[12:15], v[172:175], v[234:237], v[12:15]
	v_mfma_f32_16x16x32_bf16 v[64:67], v[136:139], v[214:217], v[64:67]
	v_mfma_f32_16x16x32_bf16 v[60:63], v[190:193], v[214:217], v[60:63]
	v_mfma_f32_16x16x32_bf16 v[48:51], v[136:139], v[222:225], v[48:51]
	v_mfma_f32_16x16x32_bf16 v[44:47], v[190:193], v[222:225], v[44:47]
	v_mfma_f32_16x16x32_bf16 v[32:35], v[136:139], v[230:233], v[32:35]
	v_mfma_f32_16x16x32_bf16 v[28:31], v[190:193], v[230:233], v[28:31]
	v_mfma_f32_16x16x32_bf16 v[16:19], v[136:139], v[238:241], v[16:19]
	v_mfma_f32_16x16x32_bf16 v[12:15], v[190:193], v[238:241], v[12:15]
	v_mfma_f32_16x16x32_bf16 v[56:59], v[194:197], v[210:213], v[56:59]
	v_mfma_f32_16x16x32_bf16 v[52:55], v[202:205], v[210:213], v[52:55]
	v_mfma_f32_16x16x32_bf16 v[40:43], v[194:197], v[218:221], v[40:43]
	v_mfma_f32_16x16x32_bf16 v[36:39], v[202:205], v[218:221], v[36:39]
	v_mfma_f32_16x16x32_bf16 v[24:27], v[194:197], v[226:229], v[24:27]
	v_mfma_f32_16x16x32_bf16 v[20:23], v[202:205], v[226:229], v[20:23]
	v_mfma_f32_16x16x32_bf16 v[8:11], v[194:197], v[234:237], v[8:11]
	v_mfma_f32_16x16x32_bf16 v[4:7], v[202:205], v[234:237], v[4:7]
	v_mfma_f32_16x16x32_bf16 v[56:59], v[198:201], v[214:217], v[56:59]
	v_mfma_f32_16x16x32_bf16 v[52:55], v[206:209], v[214:217], v[52:55]
	v_mfma_f32_16x16x32_bf16 v[40:43], v[198:201], v[222:225], v[40:43]
	v_mfma_f32_16x16x32_bf16 v[36:39], v[206:209], v[222:225], v[36:39]
	v_mfma_f32_16x16x32_bf16 v[24:27], v[198:201], v[230:233], v[24:27]
	v_mfma_f32_16x16x32_bf16 v[20:23], v[206:209], v[230:233], v[20:23]
	v_mfma_f32_16x16x32_bf16 v[8:11], v[198:201], v[238:241], v[8:11]
	v_mfma_f32_16x16x32_bf16 v[4:7], v[206:209], v[238:241], v[4:7]
	s_barrier
	s_add_u32 s50, s50, 0x100
	s_addc_u32 s51, s51, 0
	s_cmp_gt_u32 s0, 13
	s_cbranch_scc1 .LBB0_215

.LBB0_215:
	s_setprio 0
	s_and_b64 vcc, exec, s[8:9]
	s_movk_i32 s51, 0x7f
	s_cbranch_vccz .LBB0_217
	s_barrier

.LBB0_436:
	s_ashr_i32 s11, s10, 31
	s_lshl_b64 s[4:5], s[10:11], 19
	s_add_u32 s4, s19, s4
	s_addc_u32 s5, s53, s5
	s_and_b64 s[6:7], s[38:39], exec
	s_cselect_b32 s3, s5, s15
	s_cselect_b32 s11, s4, s14
	s_ashr_i32 s9, s8, 31
	s_lshl_b64 s[6:7], s[8:9], 19
	s_add_u32 s6, s54, s6
	s_addc_u32 s7, s55, s7
	s_and_b64 s[16:17], s[38:39], exec
	s_cselect_b32 s9, s7, s13
	s_cselect_b32 s22, s6, s12
	s_add_u32 s23, s12, 0x100
	s_addc_u32 s24, s13, 0
	s_add_u32 s12, s14, 0x40080
	v_mov_b32_e32 v4, 0
	s_addc_u32 s13, s15, 0
	s_mov_b32 s27, -2
	s_waitcnt lgkmcnt(0)
	s_waitcnt lgkmcnt(0)
	v_mov_b64_e32 v[4:5], 0
	v_mov_b64_e32 v[6:7], 0
	v_mov_b64_e32 v[8:9], 0
	v_mov_b64_e32 v[10:11], 0
	v_mov_b64_e32 v[12:13], 0
	v_mov_b64_e32 v[14:15], 0
	v_mov_b64_e32 v[16:17], 0
	v_mov_b64_e32 v[18:19], 0
	v_mov_b64_e32 v[20:21], 0
	v_mov_b64_e32 v[22:23], 0
	v_mov_b64_e32 v[24:25], 0
	v_mov_b64_e32 v[26:27], 0
	v_mov_b64_e32 v[28:29], 0
	v_mov_b64_e32 v[30:31], 0
	v_mov_b64_e32 v[32:33], 0
	v_mov_b64_e32 v[34:35], 0
	v_mov_b64_e32 v[36:37], 0
	v_mov_b64_e32 v[38:39], 0
	v_mov_b64_e32 v[40:41], 0
	v_mov_b64_e32 v[42:43], 0
	v_mov_b64_e32 v[44:45], 0
	v_mov_b64_e32 v[46:47], 0
	v_mov_b64_e32 v[48:49], 0
	v_mov_b64_e32 v[50:51], 0
	v_mov_b64_e32 v[52:53], 0
	v_mov_b64_e32 v[54:55], 0
	v_mov_b64_e32 v[56:57], 0
	v_mov_b64_e32 v[58:59], 0
	v_mov_b64_e32 v[60:61], 0
	v_mov_b64_e32 v[62:63], 0
	v_mov_b64_e32 v[64:65], 0
	v_mov_b64_e32 v[66:67], 0
	v_mov_b64_e32 v[68:69], 0
	v_mov_b64_e32 v[70:71], 0
	v_mov_b64_e32 v[72:73], 0
	v_mov_b64_e32 v[74:75], 0
	v_mov_b64_e32 v[76:77], 0
	v_mov_b64_e32 v[78:79], 0
	v_mov_b64_e32 v[80:81], 0
	v_mov_b64_e32 v[82:83], 0
	v_mov_b64_e32 v[84:85], 0
	v_mov_b64_e32 v[86:87], 0
	v_mov_b64_e32 v[88:89], 0
	v_mov_b64_e32 v[90:91], 0
	v_mov_b64_e32 v[92:93], 0
	v_mov_b64_e32 v[94:95], 0
	v_mov_b64_e32 v[96:97], 0
	v_mov_b64_e32 v[98:99], 0
	v_mov_b64_e32 v[100:101], 0
	v_mov_b64_e32 v[102:103], 0
	v_mov_b64_e32 v[104:105], 0
	v_mov_b64_e32 v[106:107], 0
	v_mov_b64_e32 v[108:109], 0
	v_mov_b64_e32 v[110:111], 0
	v_mov_b64_e32 v[112:113], 0
	v_mov_b64_e32 v[114:115], 0
	v_mov_b64_e32 v[116:117], 0
	v_mov_b64_e32 v[118:119], 0
	v_mov_b64_e32 v[120:121], 0
	v_mov_b64_e32 v[122:123], 0
	v_mov_b64_e32 v[124:125], 0
	v_mov_b64_e32 v[126:127], 0
	v_mov_b64_e32 v[128:129], 0
	v_mov_b64_e32 v[130:131], 0
	v_readfirstlane_b32 s35, v176
	s_nop 3
	s_lshr_b32 s35, s35, 6
	s_cmp_ge_u32 s35, 4
	s_cbranch_scc0 .Lsp_done_1
	s_setprio 1
.Lsp_done_1:
.LBB0_437:
	s_add_u32 s14, s12, 0xfffc0080
	s_addc_u32 s15, s13, -1
	s_add_i32 s28, 0, 0x10000
	s_cmp_eq_u32 s27, 12
	s_cselect_b32 s17, s3, s15
	s_cselect_b32 s16, s11, s14
	v_add_u32_e32 v152, s28, v190
	s_cselect_b32 s15, s9, s24
	s_cselect_b32 s14, s22, s23
	s_add_i32 s31, 0, 0x14000
	ds_read_b128 v[132:135], v152
	ds_read_b128 v[136:139], v152 offset:1024
	ds_read_b128 v[160:163], v152 offset:2048
	ds_read_b128 v[164:167], v152 offset:3072
	v_add_u32_e32 v152, s31, v190
	ds_read_b128 v[168:171], v152
	ds_read_b128 v[172:175], v152 offset:1024
	ds_read_b128 v[196:199], v152 offset:2048
	ds_read_b128 v[200:203], v152 offset:3072
	v_lshl_add_u64 v[152:153], s[12:13], 0, v[158:159]
	s_add_i32 m0, s51, 0xc000
	ds_read_b128 v[204:207], v194
	ds_read_b128 v[208:211], v194 offset:1024
	ds_read_b128 v[212:215], v194 offset:2048
	ds_read_b128 v[216:219], v194 offset:3072
	ds_read_b128 v[220:223], v194 offset:4096
	ds_read_b128 v[224:227], v194 offset:5120
	ds_read_b128 v[228:231], v194 offset:6144
	ds_read_b128 v[232:235], v194 offset:7168
	global_load_lds_dwordx4 v[152:153], off
	v_lshl_add_u64 v[152:153], s[12:13], 0, v[146:147]
	s_add_i32 m0, s51, 0xe000
	s_nop 0
	global_load_lds_dwordx4 v[152:153], off
	s_waitcnt vmcnt(8)
	s_waitcnt lgkmcnt(0)
	s_barrier
	s_waitcnt lgkmcnt(0)
	v_mfma_f32_16x16x32_bf16 v[128:131], v[132:135], v[204:207], v[128:131]
	v_mfma_f32_16x16x32_bf16 v[124:127], v[160:163], v[204:207], v[124:127]
	v_mfma_f32_16x16x32_bf16 v[112:115], v[132:135], v[212:215], v[112:115]
	v_mfma_f32_16x16x32_bf16 v[108:111], v[160:163], v[212:215], v[108:111]
	v_mfma_f32_16x16x32_bf16 v[96:99], v[132:135], v[220:223], v[96:99]
	v_mfma_f32_16x16x32_bf16 v[92:95], v[160:163], v[220:223], v[92:95]
	v_mfma_f32_16x16x32_bf16 v[80:83], v[132:135], v[228:231], v[80:83]
	v_mfma_f32_16x16x32_bf16 v[76:79], v[160:163], v[228:231], v[76:79]
	v_mfma_f32_16x16x32_bf16 v[128:131], v[136:139], v[208:211], v[128:131]
	v_mfma_f32_16x16x32_bf16 v[124:127], v[164:167], v[208:211], v[124:127]
	v_mfma_f32_16x16x32_bf16 v[112:115], v[136:139], v[216:219], v[112:115]
	v_mfma_f32_16x16x32_bf16 v[108:111], v[164:167], v[216:219], v[108:111]
	v_mfma_f32_16x16x32_bf16 v[96:99], v[136:139], v[224:227], v[96:99]
	v_mfma_f32_16x16x32_bf16 v[92:95], v[164:167], v[224:227], v[92:95]
	v_mfma_f32_16x16x32_bf16 v[80:83], v[136:139], v[232:235], v[80:83]
	v_mfma_f32_16x16x32_bf16 v[76:79], v[164:167], v[232:235], v[76:79]
	v_mfma_f32_16x16x32_bf16 v[120:123], v[168:171], v[204:207], v[120:123]
	v_mfma_f32_16x16x32_bf16 v[116:119], v[196:199], v[204:207], v[116:119]
	v_mfma_f32_16x16x32_bf16 v[104:107], v[168:171], v[212:215], v[104:107]
	v_mfma_f32_16x16x32_bf16 v[100:103], v[196:199], v[212:215], v[100:103]
	v_mfma_f32_16x16x32_bf16 v[88:91], v[168:171], v[220:223], v[88:91]
	v_mfma_f32_16x16x32_bf16 v[84:87], v[196:199], v[220:223], v[84:87]
	v_mfma_f32_16x16x32_bf16 v[72:75], v[168:171], v[228:231], v[72:75]
	v_mfma_f32_16x16x32_bf16 v[68:71], v[196:199], v[228:231], v[68:71]
	v_mfma_f32_16x16x32_bf16 v[120:123], v[172:175], v[208:211], v[120:123]
	v_mfma_f32_16x16x32_bf16 v[116:119], v[200:203], v[208:211], v[116:119]
	v_mfma_f32_16x16x32_bf16 v[104:107], v[172:175], v[216:219], v[104:107]
	v_mfma_f32_16x16x32_bf16 v[100:103], v[200:203], v[216:219], v[100:103]
	v_mfma_f32_16x16x32_bf16 v[88:91], v[172:175], v[224:227], v[88:91]
	v_mfma_f32_16x16x32_bf16 v[84:87], v[200:203], v[224:227], v[84:87]
	v_mfma_f32_16x16x32_bf16 v[72:75], v[172:175], v[232:235], v[72:75]
	v_mfma_f32_16x16x32_bf16 v[68:71], v[200:203], v[232:235], v[68:71]
	s_barrier
	s_add_i32 s28, s28, s58
	v_lshl_add_u64 v[152:153], s[14:15], 0, v[140:141]
	s_mov_b32 m0, s28
	ds_read_b128 v[204:207], v194 offset:16384
	ds_read_b128 v[208:211], v194 offset:17408
	ds_read_b128 v[212:215], v194 offset:18432
	ds_read_b128 v[216:219], v194 offset:19456
	ds_read_b128 v[220:223], v194 offset:20480
	ds_read_b128 v[224:227], v194 offset:21504
	ds_read_b128 v[228:231], v194 offset:22528
	ds_read_b128 v[232:235], v194 offset:23552
	global_load_lds_dwordx4 v[152:153], off
	s_add_i32 m0, s28, 0x2000
	s_add_u32 s36, s14, 0x40000
	v_lshl_add_u64 v[236:237], s[14:15], 0, v[144:145]
	s_addc_u32 s37, s15, 0
	s_add_i32 s28, s31, s58
	global_load_lds_dwordx4 v[236:237], off
	v_lshl_add_u64 v[238:239], s[36:37], 0, v[140:141]
	s_mov_b32 m0, s28
	v_lshl_add_u64 v[240:241], s[16:17], 0, v[142:143]
	global_load_lds_dwordx4 v[238:239], off
	v_lshl_add_u64 v[238:239], s[36:37], 0, v[144:145]
	s_add_i32 m0, s28, 0x2000
	s_nop 0
	global_load_lds_dwordx4 v[238:239], off
	v_lshl_add_u64 v[238:239], s[16:17], 0, v[0:1]
	s_mov_b32 m0, s51
	s_nop 0
	global_load_lds_dwordx4 v[238:239], off
	s_mov_b32 m0, s59
	s_nop 0
	global_load_lds_dwordx4 v[240:241], off
	s_waitcnt vmcnt(8)
	s_waitcnt lgkmcnt(0)
	s_barrier
	s_waitcnt lgkmcnt(0)
	v_mfma_f32_16x16x32_bf16 v[64:67], v[132:135], v[204:207], v[64:67]
	v_mfma_f32_16x16x32_bf16 v[60:63], v[160:163], v[204:207], v[60:63]
	v_mfma_f32_16x16x32_bf16 v[48:51], v[132:135], v[212:215], v[48:51]
	v_mfma_f32_16x16x32_bf16 v[44:47], v[160:163], v[212:215], v[44:47]
	v_mfma_f32_16x16x32_bf16 v[32:35], v[132:135], v[220:223], v[32:35]
	v_mfma_f32_16x16x32_bf16 v[28:31], v[160:163], v[220:223], v[28:31]
	v_mfma_f32_16x16x32_bf16 v[16:19], v[132:135], v[228:231], v[16:19]
	v_mfma_f32_16x16x32_bf16 v[12:15], v[160:163], v[228:231], v[12:15]
	v_mfma_f32_16x16x32_bf16 v[64:67], v[136:139], v[208:211], v[64:67]
	v_mfma_f32_16x16x32_bf16 v[60:63], v[164:167], v[208:211], v[60:63]
	v_mfma_f32_16x16x32_bf16 v[48:51], v[136:139], v[216:219], v[48:51]
	v_mfma_f32_16x16x32_bf16 v[44:47], v[164:167], v[216:219], v[44:47]
	v_mfma_f32_16x16x32_bf16 v[32:35], v[136:139], v[224:227], v[32:35]
	v_mfma_f32_16x16x32_bf16 v[28:31], v[164:167], v[224:227], v[28:31]
	v_mfma_f32_16x16x32_bf16 v[16:19], v[136:139], v[232:235], v[16:19]
	v_mfma_f32_16x16x32_bf16 v[12:15], v[164:167], v[232:235], v[12:15]
	v_mfma_f32_16x16x32_bf16 v[56:59], v[168:171], v[204:207], v[56:59]
	v_mfma_f32_16x16x32_bf16 v[52:55], v[196:199], v[204:207], v[52:55]
	v_mfma_f32_16x16x32_bf16 v[40:43], v[168:171], v[212:215], v[40:43]
	v_mfma_f32_16x16x32_bf16 v[36:39], v[196:199], v[212:215], v[36:39]
	v_mfma_f32_16x16x32_bf16 v[24:27], v[168:171], v[220:223], v[24:27]
	v_mfma_f32_16x16x32_bf16 v[20:23], v[196:199], v[220:223], v[20:23]
	v_mfma_f32_16x16x32_bf16 v[8:11], v[168:171], v[228:231], v[8:11]
	v_mfma_f32_16x16x32_bf16 v[4:7], v[196:199], v[228:231], v[4:7]
	v_mfma_f32_16x16x32_bf16 v[56:59], v[172:175], v[208:211], v[56:59]
	v_mfma_f32_16x16x32_bf16 v[52:55], v[200:203], v[208:211], v[52:55]
	v_mfma_f32_16x16x32_bf16 v[40:43], v[172:175], v[216:219], v[40:43]
	v_mfma_f32_16x16x32_bf16 v[36:39], v[200:203], v[216:219], v[36:39]
	v_mfma_f32_16x16x32_bf16 v[24:27], v[172:175], v[224:227], v[24:27]
	v_mfma_f32_16x16x32_bf16 v[20:23], v[200:203], v[224:227], v[20:23]
	v_mfma_f32_16x16x32_bf16 v[8:11], v[172:175], v[232:235], v[8:11]
	v_mfma_f32_16x16x32_bf16 v[4:7], v[200:203], v[232:235], v[4:7]
	s_barrier
	s_add_i32 s28, 0, 0x18000
	s_add_i32 s31, 0, 0x1c000
	v_add_u32_e32 v164, s28, v190
	v_add_u32_e32 v195, s31, v190
	ds_read_b128 v[132:135], v164
	ds_read_b128 v[136:139], v164 offset:1024
	ds_read_b128 v[160:163], v164 offset:2048
	ds_read_b128 v[164:167], v164 offset:3072
	ds_read_b128 v[168:171], v195
	ds_read_b128 v[172:175], v195 offset:1024
	ds_read_b128 v[196:199], v195 offset:2048
	ds_read_b128 v[200:203], v195 offset:3072
	s_add_u32 s16, s16, 0x40000
	s_addc_u32 s17, s17, 0
	s_mov_b32 m0, s52
	v_lshl_add_u64 v[242:243], s[16:17], 0, v[0:1]
	ds_read_b128 v[204:207], v194 offset:32768
	ds_read_b128 v[208:211], v194 offset:33792
	ds_read_b128 v[212:215], v194 offset:34816
	ds_read_b128 v[216:219], v194 offset:35840
	ds_read_b128 v[220:223], v194 offset:36864
	ds_read_b128 v[224:227], v194 offset:37888
	ds_read_b128 v[228:231], v194 offset:38912
	ds_read_b128 v[232:235], v194 offset:39936
	global_load_lds_dwordx4 v[242:243], off
	v_lshl_add_u64 v[242:243], s[16:17], 0, v[142:143]
	s_mov_b32 m0, s71
	s_nop 0
	global_load_lds_dwordx4 v[242:243], off
	s_waitcnt vmcnt(8)
	s_waitcnt lgkmcnt(0)
	s_barrier
	s_waitcnt lgkmcnt(0)
	v_mfma_f32_16x16x32_bf16 v[128:131], v[132:135], v[204:207], v[128:131]
	v_mfma_f32_16x16x32_bf16 v[124:127], v[160:163], v[204:207], v[124:127]
	v_mfma_f32_16x16x32_bf16 v[112:115], v[132:135], v[212:215], v[112:115]
	v_mfma_f32_16x16x32_bf16 v[108:111], v[160:163], v[212:215], v[108:111]
	v_mfma_f32_16x16x32_bf16 v[96:99], v[132:135], v[220:223], v[96:99]
	v_mfma_f32_16x16x32_bf16 v[92:95], v[160:163], v[220:223], v[92:95]
	v_mfma_f32_16x16x32_bf16 v[80:83], v[132:135], v[228:231], v[80:83]
	v_mfma_f32_16x16x32_bf16 v[76:79], v[160:163], v[228:231], v[76:79]
	v_mfma_f32_16x16x32_bf16 v[128:131], v[136:139], v[208:211], v[128:131]
	v_mfma_f32_16x16x32_bf16 v[124:127], v[164:167], v[208:211], v[124:127]
	v_mfma_f32_16x16x32_bf16 v[112:115], v[136:139], v[216:219], v[112:115]
	v_mfma_f32_16x16x32_bf16 v[108:111], v[164:167], v[216:219], v[108:111]
	v_mfma_f32_16x16x32_bf16 v[96:99], v[136:139], v[224:227], v[96:99]
	v_mfma_f32_16x16x32_bf16 v[92:95], v[164:167], v[224:227], v[92:95]
	v_mfma_f32_16x16x32_bf16 v[80:83], v[136:139], v[232:235], v[80:83]
	v_mfma_f32_16x16x32_bf16 v[76:79], v[164:167], v[232:235], v[76:79]
	v_mfma_f32_16x16x32_bf16 v[120:123], v[168:171], v[204:207], v[120:123]
	v_mfma_f32_16x16x32_bf16 v[116:119], v[196:199], v[204:207], v[116:119]
	v_mfma_f32_16x16x32_bf16 v[104:107], v[168:171], v[212:215], v[104:107]
	v_mfma_f32_16x16x32_bf16 v[100:103], v[196:199], v[212:215], v[100:103]
	v_mfma_f32_16x16x32_bf16 v[88:91], v[168:171], v[220:223], v[88:91]
	v_mfma_f32_16x16x32_bf16 v[84:87], v[196:199], v[220:223], v[84:87]
	v_mfma_f32_16x16x32_bf16 v[72:75], v[168:171], v[228:231], v[72:75]
	v_mfma_f32_16x16x32_bf16 v[68:71], v[196:199], v[228:231], v[68:71]
	v_mfma_f32_16x16x32_bf16 v[120:123], v[172:175], v[208:211], v[120:123]
	v_mfma_f32_16x16x32_bf16 v[116:119], v[200:203], v[208:211], v[116:119]
	v_mfma_f32_16x16x32_bf16 v[104:107], v[172:175], v[216:219], v[104:107]
	v_mfma_f32_16x16x32_bf16 v[100:103], v[200:203], v[216:219], v[100:103]
	v_mfma_f32_16x16x32_bf16 v[88:91], v[172:175], v[224:227], v[88:91]
	v_mfma_f32_16x16x32_bf16 v[84:87], v[200:203], v[224:227], v[84:87]
	v_mfma_f32_16x16x32_bf16 v[72:75], v[172:175], v[232:235], v[72:75]
	v_mfma_f32_16x16x32_bf16 v[68:71], v[200:203], v[232:235], v[68:71]
	s_barrier
	s_add_i32 s16, s28, s58
	v_lshl_add_u64 v[152:153], v[152:153], 0, s[84:85]
	s_mov_b32 m0, s16
	ds_read_b128 v[204:207], v194 offset:49152
	ds_read_b128 v[208:211], v194 offset:50176
	ds_read_b128 v[212:215], v194 offset:51200
	ds_read_b128 v[216:219], v194 offset:52224
	ds_read_b128 v[220:223], v194 offset:53248
	ds_read_b128 v[224:227], v194 offset:54272
	ds_read_b128 v[228:231], v194 offset:55296
	ds_read_b128 v[232:235], v194 offset:56320
	global_load_lds_dwordx4 v[152:153], off
	s_add_i32 m0, s16, 0x2000
	s_add_u32 s14, s14, 0x40080
	v_lshl_add_u64 v[152:153], v[236:237], 0, s[84:85]
	s_addc_u32 s15, s15, 0
	s_add_i32 s16, s31, s58
	global_load_lds_dwordx4 v[152:153], off
	v_lshl_add_u64 v[152:153], s[14:15], 0, v[140:141]
	s_mov_b32 m0, s16
	s_nop 0
	global_load_lds_dwordx4 v[152:153], off
	v_lshl_add_u64 v[152:153], s[14:15], 0, v[144:145]
	s_add_i32 m0, s16, 0x2000
	s_nop 0
	global_load_lds_dwordx4 v[152:153], off
	v_lshl_add_u64 v[152:153], v[238:239], 0, s[84:85]
	s_mov_b32 m0, s18
	s_nop 0
	global_load_lds_dwordx4 v[152:153], off
	v_lshl_add_u64 v[152:153], v[240:241], 0, s[84:85]
	s_mov_b32 m0, s46
	s_nop 0
	global_load_lds_dwordx4 v[152:153], off
	s_waitcnt vmcnt(8)
	s_waitcnt lgkmcnt(0)
	s_barrier
	s_waitcnt lgkmcnt(0)
	v_mfma_f32_16x16x32_bf16 v[64:67], v[132:135], v[204:207], v[64:67]
	v_mfma_f32_16x16x32_bf16 v[60:63], v[160:163], v[204:207], v[60:63]
	v_mfma_f32_16x16x32_bf16 v[48:51], v[132:135], v[212:215], v[48:51]
	v_mfma_f32_16x16x32_bf16 v[44:47], v[160:163], v[212:215], v[44:47]
	v_mfma_f32_16x16x32_bf16 v[32:35], v[132:135], v[220:223], v[32:35]
	v_mfma_f32_16x16x32_bf16 v[28:31], v[160:163], v[220:223], v[28:31]
	v_mfma_f32_16x16x32_bf16 v[16:19], v[132:135], v[228:231], v[16:19]
	v_mfma_f32_16x16x32_bf16 v[12:15], v[160:163], v[228:231], v[12:15]
	v_mfma_f32_16x16x32_bf16 v[64:67], v[136:139], v[208:211], v[64:67]
	v_mfma_f32_16x16x32_bf16 v[60:63], v[164:167], v[208:211], v[60:63]
	v_mfma_f32_16x16x32_bf16 v[48:51], v[136:139], v[216:219], v[48:51]
	v_mfma_f32_16x16x32_bf16 v[44:47], v[164:167], v[216:219], v[44:47]
	v_mfma_f32_16x16x32_bf16 v[32:35], v[136:139], v[224:227], v[32:35]
	v_mfma_f32_16x16x32_bf16 v[28:31], v[164:167], v[224:227], v[28:31]
	v_mfma_f32_16x16x32_bf16 v[16:19], v[136:139], v[232:235], v[16:19]
	v_mfma_f32_16x16x32_bf16 v[12:15], v[164:167], v[232:235], v[12:15]
	v_mfma_f32_16x16x32_bf16 v[56:59], v[168:171], v[204:207], v[56:59]
	v_mfma_f32_16x16x32_bf16 v[52:55], v[196:199], v[204:207], v[52:55]
	v_mfma_f32_16x16x32_bf16 v[40:43], v[168:171], v[212:215], v[40:43]
	v_mfma_f32_16x16x32_bf16 v[36:39], v[196:199], v[212:215], v[36:39]
	v_mfma_f32_16x16x32_bf16 v[24:27], v[168:171], v[220:223], v[24:27]
	v_mfma_f32_16x16x32_bf16 v[20:23], v[196:199], v[220:223], v[20:23]
	v_mfma_f32_16x16x32_bf16 v[8:11], v[168:171], v[228:231], v[8:11]
	v_mfma_f32_16x16x32_bf16 v[4:7], v[196:199], v[228:231], v[4:7]
	v_mfma_f32_16x16x32_bf16 v[56:59], v[172:175], v[208:211], v[56:59]
	v_mfma_f32_16x16x32_bf16 v[52:55], v[200:203], v[208:211], v[52:55]
	v_mfma_f32_16x16x32_bf16 v[40:43], v[172:175], v[216:219], v[40:43]
	v_mfma_f32_16x16x32_bf16 v[36:39], v[200:203], v[216:219], v[36:39]
	v_mfma_f32_16x16x32_bf16 v[24:27], v[172:175], v[224:227], v[24:27]
	v_mfma_f32_16x16x32_bf16 v[20:23], v[200:203], v[224:227], v[20:23]
	v_mfma_f32_16x16x32_bf16 v[8:11], v[172:175], v[232:235], v[8:11]
	v_mfma_f32_16x16x32_bf16 v[4:7], v[200:203], v[232:235], v[4:7]
	s_barrier
	s_add_i32 s27, s27, 2
	s_add_u32 s23, s23, 0x100
	s_addc_u32 s24, s24, 0
	s_add_u32 s12, s12, 0x100
	s_addc_u32 s13, s13, 0
	s_cmp_gt_u32 s27, 13
	s_cbranch_scc0 .LBB0_437
	s_setprio 0
	s_and_b64 vcc, exec, s[48:49]
	s_cbranch_vccz .LBB0_440
	s_barrier

.LBB0_619:
	s_ashr_i32 s41, s40, 31
	s_lshl_b64 s[16:17], s[40:41], 19
	s_add_u32 s42, s48, s16
	s_addc_u32 s43, s49, s17
	s_and_b64 s[16:17], s[38:39], exec
	s_cselect_b32 s11, s43, s47
	s_cselect_b32 s22, s42, s46
	s_ashr_i32 s9, s8, 31
	s_lshl_b64 s[16:17], s[8:9], 19
	s_add_u32 s44, s50, s16
	s_addc_u32 s45, s51, s17
	s_and_b64 s[16:17], s[38:39], exec
	s_cselect_b32 s9, s45, s15
	s_cselect_b32 s28, s44, s14
	s_add_u32 s23, s14, 0x100
	s_addc_u32 s24, s15, 0
	s_add_u32 s14, s46, 0x40080
	v_mov_b32_e32 v4, 0
	s_addc_u32 s15, s47, 0
	s_mov_b32 s27, -2
	s_waitcnt lgkmcnt(0)
	s_waitcnt lgkmcnt(0)
	v_mov_b64_e32 v[4:5], 0
	v_mov_b64_e32 v[6:7], 0
	v_mov_b64_e32 v[8:9], 0
	v_mov_b64_e32 v[10:11], 0
	v_mov_b64_e32 v[12:13], 0
	v_mov_b64_e32 v[14:15], 0
	v_mov_b64_e32 v[16:17], 0
	v_mov_b64_e32 v[18:19], 0
	v_mov_b64_e32 v[20:21], 0
	v_mov_b64_e32 v[22:23], 0
	v_mov_b64_e32 v[24:25], 0
	v_mov_b64_e32 v[26:27], 0
	v_mov_b64_e32 v[28:29], 0
	v_mov_b64_e32 v[30:31], 0
	v_mov_b64_e32 v[32:33], 0
	v_mov_b64_e32 v[34:35], 0
	v_mov_b64_e32 v[36:37], 0
	v_mov_b64_e32 v[38:39], 0
	v_mov_b64_e32 v[40:41], 0
	v_mov_b64_e32 v[42:43], 0
	v_mov_b64_e32 v[44:45], 0
	v_mov_b64_e32 v[46:47], 0
	v_mov_b64_e32 v[48:49], 0
	v_mov_b64_e32 v[50:51], 0
	v_mov_b64_e32 v[52:53], 0
	v_mov_b64_e32 v[54:55], 0
	v_mov_b64_e32 v[56:57], 0
	v_mov_b64_e32 v[58:59], 0
	v_mov_b64_e32 v[60:61], 0
	v_mov_b64_e32 v[62:63], 0
	v_mov_b64_e32 v[64:65], 0
	v_mov_b64_e32 v[66:67], 0
	v_mov_b64_e32 v[68:69], 0
	v_mov_b64_e32 v[70:71], 0
	v_mov_b64_e32 v[72:73], 0
	v_mov_b64_e32 v[74:75], 0
	v_mov_b64_e32 v[76:77], 0
	v_mov_b64_e32 v[78:79], 0
	v_mov_b64_e32 v[80:81], 0
	v_mov_b64_e32 v[82:83], 0
	v_mov_b64_e32 v[84:85], 0
	v_mov_b64_e32 v[86:87], 0
	v_mov_b64_e32 v[88:89], 0
	v_mov_b64_e32 v[90:91], 0
	v_mov_b64_e32 v[92:93], 0
	v_mov_b64_e32 v[94:95], 0
	v_mov_b64_e32 v[96:97], 0
	v_mov_b64_e32 v[98:99], 0
	v_mov_b64_e32 v[100:101], 0
	v_mov_b64_e32 v[102:103], 0
	v_mov_b64_e32 v[104:105], 0
	v_mov_b64_e32 v[106:107], 0
	v_mov_b64_e32 v[108:109], 0
	v_mov_b64_e32 v[110:111], 0
	v_mov_b64_e32 v[112:113], 0
	v_mov_b64_e32 v[114:115], 0
	v_mov_b64_e32 v[116:117], 0
	v_mov_b64_e32 v[118:119], 0
	v_mov_b64_e32 v[120:121], 0
	v_mov_b64_e32 v[122:123], 0
	v_mov_b64_e32 v[124:125], 0
	v_mov_b64_e32 v[126:127], 0
	v_mov_b64_e32 v[128:129], 0
	v_mov_b64_e32 v[130:131], 0
	v_readfirstlane_b32 s35, v176
	s_nop 3
	s_lshr_b32 s35, s35, 6
	s_cmp_ge_u32 s35, 4
	s_cbranch_scc0 .Lsp_done_2
	s_setprio 1
.Lsp_done_2:
.LBB0_620:
	s_add_u32 s16, s14, 0xfffc0080
	s_addc_u32 s17, s15, -1
	s_add_i32 s31, 0, 0x10000
	s_cmp_eq_u32 s27, 12
	s_cselect_b32 s19, s11, s17
	s_cselect_b32 s18, s22, s16
	v_add_u32_e32 v152, s31, v146
	s_cselect_b32 s17, s9, s24
	s_cselect_b32 s16, s28, s23
	s_add_i32 s41, 0, 0x14000
	ds_read_b128 v[142:145], v152
	ds_read_b128 v[160:163], v152 offset:1024
	ds_read_b128 v[164:167], v152 offset:2048
	ds_read_b128 v[168:171], v152 offset:3072
	v_add_u32_e32 v152, s41, v146
	ds_read_b128 v[172:175], v152
	ds_read_b128 v[190:193], v152 offset:1024
	ds_read_b128 v[194:197], v152 offset:2048
	ds_read_b128 v[198:201], v152 offset:3072
	v_lshl_add_u64 v[152:153], s[14:15], 0, v[140:141]
	s_add_i32 m0, s13, 0xc000
	ds_read_b128 v[202:205], v158
	ds_read_b128 v[206:209], v158 offset:1024
	ds_read_b128 v[210:213], v158 offset:2048
	ds_read_b128 v[214:217], v158 offset:3072
	ds_read_b128 v[218:221], v158 offset:4096
	ds_read_b128 v[222:225], v158 offset:5120
	ds_read_b128 v[226:229], v158 offset:6144
	ds_read_b128 v[230:233], v158 offset:7168
	global_load_lds_dwordx4 v[152:153], off
	v_lshl_add_u64 v[152:153], s[14:15], 0, v[138:139]
	s_add_i32 m0, s13, 0xe000
	s_nop 0
	global_load_lds_dwordx4 v[152:153], off
	s_waitcnt vmcnt(8)
	s_waitcnt lgkmcnt(0)
	s_barrier
	s_waitcnt lgkmcnt(0)
	v_mfma_f32_16x16x32_bf16 v[128:131], v[142:145], v[202:205], v[128:131]
	v_mfma_f32_16x16x32_bf16 v[120:123], v[164:167], v[202:205], v[120:123]
	v_mfma_f32_16x16x32_bf16 v[112:115], v[142:145], v[210:213], v[112:115]
	v_mfma_f32_16x16x32_bf16 v[104:107], v[164:167], v[210:213], v[104:107]
	v_mfma_f32_16x16x32_bf16 v[96:99], v[142:145], v[218:221], v[96:99]
	v_mfma_f32_16x16x32_bf16 v[88:91], v[164:167], v[218:221], v[88:91]
	v_mfma_f32_16x16x32_bf16 v[80:83], v[142:145], v[226:229], v[80:83]
	v_mfma_f32_16x16x32_bf16 v[72:75], v[164:167], v[226:229], v[72:75]
	v_mfma_f32_16x16x32_bf16 v[128:131], v[160:163], v[206:209], v[128:131]
	v_mfma_f32_16x16x32_bf16 v[120:123], v[168:171], v[206:209], v[120:123]
	v_mfma_f32_16x16x32_bf16 v[112:115], v[160:163], v[214:217], v[112:115]
	v_mfma_f32_16x16x32_bf16 v[104:107], v[168:171], v[214:217], v[104:107]
	v_mfma_f32_16x16x32_bf16 v[96:99], v[160:163], v[222:225], v[96:99]
	v_mfma_f32_16x16x32_bf16 v[88:91], v[168:171], v[222:225], v[88:91]
	v_mfma_f32_16x16x32_bf16 v[80:83], v[160:163], v[230:233], v[80:83]
	v_mfma_f32_16x16x32_bf16 v[72:75], v[168:171], v[230:233], v[72:75]
	v_mfma_f32_16x16x32_bf16 v[124:127], v[172:175], v[202:205], v[124:127]
	v_mfma_f32_16x16x32_bf16 v[116:119], v[194:197], v[202:205], v[116:119]
	v_mfma_f32_16x16x32_bf16 v[108:111], v[172:175], v[210:213], v[108:111]
	v_mfma_f32_16x16x32_bf16 v[100:103], v[194:197], v[210:213], v[100:103]
	v_mfma_f32_16x16x32_bf16 v[92:95], v[172:175], v[218:221], v[92:95]
	v_mfma_f32_16x16x32_bf16 v[84:87], v[194:197], v[218:221], v[84:87]
	v_mfma_f32_16x16x32_bf16 v[76:79], v[172:175], v[226:229], v[76:79]
	v_mfma_f32_16x16x32_bf16 v[68:71], v[194:197], v[226:229], v[68:71]
	v_mfma_f32_16x16x32_bf16 v[124:127], v[190:193], v[206:209], v[124:127]
	v_mfma_f32_16x16x32_bf16 v[116:119], v[198:201], v[206:209], v[116:119]
	v_mfma_f32_16x16x32_bf16 v[108:111], v[190:193], v[214:217], v[108:111]
	v_mfma_f32_16x16x32_bf16 v[100:103], v[198:201], v[214:217], v[100:103]
	v_mfma_f32_16x16x32_bf16 v[92:95], v[190:193], v[222:225], v[92:95]
	v_mfma_f32_16x16x32_bf16 v[84:87], v[198:201], v[222:225], v[84:87]
	v_mfma_f32_16x16x32_bf16 v[76:79], v[190:193], v[230:233], v[76:79]
	v_mfma_f32_16x16x32_bf16 v[68:71], v[198:201], v[230:233], v[68:71]
	s_barrier
	s_add_i32 s31, s31, s52
	v_lshl_add_u64 v[152:153], s[16:17], 0, v[132:133]
	s_mov_b32 m0, s31
	ds_read_b128 v[202:205], v158 offset:16384
	ds_read_b128 v[206:209], v158 offset:17408
	ds_read_b128 v[210:213], v158 offset:18432
	ds_read_b128 v[214:217], v158 offset:19456
	ds_read_b128 v[218:221], v158 offset:20480
	ds_read_b128 v[222:225], v158 offset:21504
	ds_read_b128 v[226:229], v158 offset:22528
	ds_read_b128 v[230:233], v158 offset:23552
	global_load_lds_dwordx4 v[152:153], off
	s_add_i32 m0, s31, 0x2000
	s_add_u32 s36, s16, 0x40000
	v_lshl_add_u64 v[234:235], s[16:17], 0, v[136:137]
	s_addc_u32 s37, s17, 0
	s_add_i32 s31, s41, s52
	global_load_lds_dwordx4 v[234:235], off
	v_lshl_add_u64 v[236:237], s[36:37], 0, v[132:133]
	s_mov_b32 m0, s31
	v_lshl_add_u64 v[238:239], s[18:19], 0, v[134:135]
	global_load_lds_dwordx4 v[236:237], off
	v_lshl_add_u64 v[236:237], s[36:37], 0, v[136:137]
	s_add_i32 m0, s31, 0x2000
	s_nop 0
	global_load_lds_dwordx4 v[236:237], off
	v_lshl_add_u64 v[236:237], s[18:19], 0, v[0:1]
	s_mov_b32 m0, s13
	s_nop 0
	global_load_lds_dwordx4 v[236:237], off
	s_mov_b32 m0, s53
	s_nop 0
	global_load_lds_dwordx4 v[238:239], off
	s_waitcnt vmcnt(8)
	s_waitcnt lgkmcnt(0)
	s_barrier
	s_waitcnt lgkmcnt(0)
	v_mfma_f32_16x16x32_bf16 v[64:67], v[142:145], v[202:205], v[64:67]
	v_mfma_f32_16x16x32_bf16 v[56:59], v[164:167], v[202:205], v[56:59]
	v_mfma_f32_16x16x32_bf16 v[48:51], v[142:145], v[210:213], v[48:51]
	v_mfma_f32_16x16x32_bf16 v[40:43], v[164:167], v[210:213], v[40:43]
	v_mfma_f32_16x16x32_bf16 v[32:35], v[142:145], v[218:221], v[32:35]
	v_mfma_f32_16x16x32_bf16 v[24:27], v[164:167], v[218:221], v[24:27]
	v_mfma_f32_16x16x32_bf16 v[16:19], v[142:145], v[226:229], v[16:19]
	v_mfma_f32_16x16x32_bf16 v[8:11], v[164:167], v[226:229], v[8:11]
	v_mfma_f32_16x16x32_bf16 v[64:67], v[160:163], v[206:209], v[64:67]
	v_mfma_f32_16x16x32_bf16 v[56:59], v[168:171], v[206:209], v[56:59]
	v_mfma_f32_16x16x32_bf16 v[48:51], v[160:163], v[214:217], v[48:51]
	v_mfma_f32_16x16x32_bf16 v[40:43], v[168:171], v[214:217], v[40:43]
	v_mfma_f32_16x16x32_bf16 v[32:35], v[160:163], v[222:225], v[32:35]
	v_mfma_f32_16x16x32_bf16 v[24:27], v[168:171], v[222:225], v[24:27]
	v_mfma_f32_16x16x32_bf16 v[16:19], v[160:163], v[230:233], v[16:19]
	v_mfma_f32_16x16x32_bf16 v[8:11], v[168:171], v[230:233], v[8:11]
	v_mfma_f32_16x16x32_bf16 v[60:63], v[172:175], v[202:205], v[60:63]
	v_mfma_f32_16x16x32_bf16 v[52:55], v[194:197], v[202:205], v[52:55]
	v_mfma_f32_16x16x32_bf16 v[44:47], v[172:175], v[210:213], v[44:47]
	v_mfma_f32_16x16x32_bf16 v[36:39], v[194:197], v[210:213], v[36:39]
	v_mfma_f32_16x16x32_bf16 v[28:31], v[172:175], v[218:221], v[28:31]
	v_mfma_f32_16x16x32_bf16 v[20:23], v[194:197], v[218:221], v[20:23]
	v_mfma_f32_16x16x32_bf16 v[12:15], v[172:175], v[226:229], v[12:15]
	v_mfma_f32_16x16x32_bf16 v[4:7], v[194:197], v[226:229], v[4:7]
	v_mfma_f32_16x16x32_bf16 v[60:63], v[190:193], v[206:209], v[60:63]
	v_mfma_f32_16x16x32_bf16 v[52:55], v[198:201], v[206:209], v[52:55]
	v_mfma_f32_16x16x32_bf16 v[44:47], v[190:193], v[214:217], v[44:47]
	v_mfma_f32_16x16x32_bf16 v[36:39], v[198:201], v[214:217], v[36:39]
	v_mfma_f32_16x16x32_bf16 v[28:31], v[190:193], v[222:225], v[28:31]
	v_mfma_f32_16x16x32_bf16 v[20:23], v[198:201], v[222:225], v[20:23]
	v_mfma_f32_16x16x32_bf16 v[12:15], v[190:193], v[230:233], v[12:15]
	v_mfma_f32_16x16x32_bf16 v[4:7], v[198:201], v[230:233], v[4:7]
	s_barrier
	s_add_i32 s31, 0, 0x18000
	v_add_u32_e32 v159, s31, v146
	s_add_i32 s36, 0, 0x1c000
	ds_read_b128 v[142:145], v159
	ds_read_b128 v[160:163], v159 offset:1024
	ds_read_b128 v[164:167], v159 offset:2048
	ds_read_b128 v[168:171], v159 offset:3072
	v_add_u32_e32 v159, s36, v146
	ds_read_b128 v[172:175], v159
	ds_read_b128 v[190:193], v159 offset:1024
	ds_read_b128 v[194:197], v159 offset:2048
	ds_read_b128 v[198:201], v159 offset:3072
	s_add_u32 s18, s18, 0x40000
	s_addc_u32 s19, s19, 0
	s_mov_b32 m0, s54
	v_lshl_add_u64 v[240:241], s[18:19], 0, v[0:1]
	ds_read_b128 v[202:205], v158 offset:32768
	ds_read_b128 v[206:209], v158 offset:33792
	ds_read_b128 v[210:213], v158 offset:34816
	ds_read_b128 v[214:217], v158 offset:35840
	ds_read_b128 v[218:221], v158 offset:36864
	ds_read_b128 v[222:225], v158 offset:37888
	ds_read_b128 v[226:229], v158 offset:38912
	ds_read_b128 v[230:233], v158 offset:39936
	global_load_lds_dwordx4 v[240:241], off
	v_lshl_add_u64 v[240:241], s[18:19], 0, v[134:135]
	s_mov_b32 m0, s55
	s_nop 0
	global_load_lds_dwordx4 v[240:241], off
	s_waitcnt vmcnt(8)
	s_waitcnt lgkmcnt(0)
	s_barrier
	s_waitcnt lgkmcnt(0)
	v_mfma_f32_16x16x32_bf16 v[128:131], v[142:145], v[202:205], v[128:131]
	v_mfma_f32_16x16x32_bf16 v[120:123], v[164:167], v[202:205], v[120:123]
	v_mfma_f32_16x16x32_bf16 v[112:115], v[142:145], v[210:213], v[112:115]
	v_mfma_f32_16x16x32_bf16 v[104:107], v[164:167], v[210:213], v[104:107]
	v_mfma_f32_16x16x32_bf16 v[96:99], v[142:145], v[218:221], v[96:99]
	v_mfma_f32_16x16x32_bf16 v[88:91], v[164:167], v[218:221], v[88:91]
	v_mfma_f32_16x16x32_bf16 v[80:83], v[142:145], v[226:229], v[80:83]
	v_mfma_f32_16x16x32_bf16 v[72:75], v[164:167], v[226:229], v[72:75]
	v_mfma_f32_16x16x32_bf16 v[128:131], v[160:163], v[206:209], v[128:131]
	v_mfma_f32_16x16x32_bf16 v[120:123], v[168:171], v[206:209], v[120:123]
	v_mfma_f32_16x16x32_bf16 v[112:115], v[160:163], v[214:217], v[112:115]
	v_mfma_f32_16x16x32_bf16 v[104:107], v[168:171], v[214:217], v[104:107]
	v_mfma_f32_16x16x32_bf16 v[96:99], v[160:163], v[222:225], v[96:99]
	v_mfma_f32_16x16x32_bf16 v[88:91], v[168:171], v[222:225], v[88:91]
	v_mfma_f32_16x16x32_bf16 v[80:83], v[160:163], v[230:233], v[80:83]
	v_mfma_f32_16x16x32_bf16 v[72:75], v[168:171], v[230:233], v[72:75]
	v_mfma_f32_16x16x32_bf16 v[124:127], v[172:175], v[202:205], v[124:127]
	v_mfma_f32_16x16x32_bf16 v[116:119], v[194:197], v[202:205], v[116:119]
	v_mfma_f32_16x16x32_bf16 v[108:111], v[172:175], v[210:213], v[108:111]
	v_mfma_f32_16x16x32_bf16 v[100:103], v[194:197], v[210:213], v[100:103]
	v_mfma_f32_16x16x32_bf16 v[92:95], v[172:175], v[218:221], v[92:95]
	v_mfma_f32_16x16x32_bf16 v[84:87], v[194:197], v[218:221], v[84:87]
	v_mfma_f32_16x16x32_bf16 v[76:79], v[172:175], v[226:229], v[76:79]
	v_mfma_f32_16x16x32_bf16 v[68:71], v[194:197], v[226:229], v[68:71]
	v_mfma_f32_16x16x32_bf16 v[124:127], v[190:193], v[206:209], v[124:127]
	v_mfma_f32_16x16x32_bf16 v[116:119], v[198:201], v[206:209], v[116:119]
	v_mfma_f32_16x16x32_bf16 v[108:111], v[190:193], v[214:217], v[108:111]
	v_mfma_f32_16x16x32_bf16 v[100:103], v[198:201], v[214:217], v[100:103]
	v_mfma_f32_16x16x32_bf16 v[92:95], v[190:193], v[222:225], v[92:95]
	v_mfma_f32_16x16x32_bf16 v[84:87], v[198:201], v[222:225], v[84:87]
	v_mfma_f32_16x16x32_bf16 v[76:79], v[190:193], v[230:233], v[76:79]
	v_mfma_f32_16x16x32_bf16 v[68:71], v[198:201], v[230:233], v[68:71]
	s_barrier
	s_add_i32 s18, s31, s52
	v_lshl_add_u64 v[152:153], v[152:153], 0, s[84:85]
	s_mov_b32 m0, s18
	ds_read_b128 v[202:205], v158 offset:49152
	ds_read_b128 v[206:209], v158 offset:50176
	ds_read_b128 v[210:213], v158 offset:51200
	ds_read_b128 v[214:217], v158 offset:52224
	ds_read_b128 v[218:221], v158 offset:53248
	ds_read_b128 v[222:225], v158 offset:54272
	ds_read_b128 v[226:229], v158 offset:55296
	ds_read_b128 v[230:233], v158 offset:56320
	global_load_lds_dwordx4 v[152:153], off
	s_add_i32 m0, s18, 0x2000
	s_add_u32 s16, s16, 0x40080
	v_lshl_add_u64 v[152:153], v[234:235], 0, s[84:85]
	s_addc_u32 s17, s17, 0
	s_add_i32 s18, s36, s52
	global_load_lds_dwordx4 v[152:153], off
	v_lshl_add_u64 v[152:153], s[16:17], 0, v[132:133]
	s_mov_b32 m0, s18
	s_nop 0
	global_load_lds_dwordx4 v[152:153], off
	v_lshl_add_u64 v[152:153], s[16:17], 0, v[136:137]
	s_add_i32 m0, s18, 0x2000
	s_nop 0
	global_load_lds_dwordx4 v[152:153], off
	v_lshl_add_u64 v[152:153], v[236:237], 0, s[84:85]
	s_mov_b32 m0, s58
	s_nop 0
	global_load_lds_dwordx4 v[152:153], off
	v_lshl_add_u64 v[152:153], v[238:239], 0, s[84:85]
	s_mov_b32 m0, s59
	s_nop 0
	global_load_lds_dwordx4 v[152:153], off
	s_waitcnt vmcnt(8)
	s_waitcnt lgkmcnt(0)
	s_barrier
	s_waitcnt lgkmcnt(0)
	v_mfma_f32_16x16x32_bf16 v[64:67], v[142:145], v[202:205], v[64:67]
	v_mfma_f32_16x16x32_bf16 v[56:59], v[164:167], v[202:205], v[56:59]
	v_mfma_f32_16x16x32_bf16 v[48:51], v[142:145], v[210:213], v[48:51]
	v_mfma_f32_16x16x32_bf16 v[40:43], v[164:167], v[210:213], v[40:43]
	v_mfma_f32_16x16x32_bf16 v[32:35], v[142:145], v[218:221], v[32:35]
	v_mfma_f32_16x16x32_bf16 v[24:27], v[164:167], v[218:221], v[24:27]
	v_mfma_f32_16x16x32_bf16 v[16:19], v[142:145], v[226:229], v[16:19]
	v_mfma_f32_16x16x32_bf16 v[8:11], v[164:167], v[226:229], v[8:11]
	v_mfma_f32_16x16x32_bf16 v[64:67], v[160:163], v[206:209], v[64:67]
	v_mfma_f32_16x16x32_bf16 v[56:59], v[168:171], v[206:209], v[56:59]
	v_mfma_f32_16x16x32_bf16 v[48:51], v[160:163], v[214:217], v[48:51]
	v_mfma_f32_16x16x32_bf16 v[40:43], v[168:171], v[214:217], v[40:43]
	v_mfma_f32_16x16x32_bf16 v[32:35], v[160:163], v[222:225], v[32:35]
	v_mfma_f32_16x16x32_bf16 v[24:27], v[168:171], v[222:225], v[24:27]
	v_mfma_f32_16x16x32_bf16 v[16:19], v[160:163], v[230:233], v[16:19]
	v_mfma_f32_16x16x32_bf16 v[8:11], v[168:171], v[230:233], v[8:11]
	v_mfma_f32_16x16x32_bf16 v[60:63], v[172:175], v[202:205], v[60:63]
	v_mfma_f32_16x16x32_bf16 v[52:55], v[194:197], v[202:205], v[52:55]
	v_mfma_f32_16x16x32_bf16 v[44:47], v[172:175], v[210:213], v[44:47]
	v_mfma_f32_16x16x32_bf16 v[36:39], v[194:197], v[210:213], v[36:39]
	v_mfma_f32_16x16x32_bf16 v[28:31], v[172:175], v[218:221], v[28:31]
	v_mfma_f32_16x16x32_bf16 v[20:23], v[194:197], v[218:221], v[20:23]
	v_mfma_f32_16x16x32_bf16 v[12:15], v[172:175], v[226:229], v[12:15]
	v_mfma_f32_16x16x32_bf16 v[4:7], v[194:197], v[226:229], v[4:7]
	v_mfma_f32_16x16x32_bf16 v[60:63], v[190:193], v[206:209], v[60:63]
	v_mfma_f32_16x16x32_bf16 v[52:55], v[198:201], v[206:209], v[52:55]
	v_mfma_f32_16x16x32_bf16 v[44:47], v[190:193], v[214:217], v[44:47]
	v_mfma_f32_16x16x32_bf16 v[36:39], v[198:201], v[214:217], v[36:39]
	v_mfma_f32_16x16x32_bf16 v[28:31], v[190:193], v[222:225], v[28:31]
	v_mfma_f32_16x16x32_bf16 v[20:23], v[198:201], v[222:225], v[20:23]
	v_mfma_f32_16x16x32_bf16 v[12:15], v[190:193], v[230:233], v[12:15]
	v_mfma_f32_16x16x32_bf16 v[4:7], v[198:201], v[230:233], v[4:7]
	s_barrier
	s_add_i32 s27, s27, 2
	s_add_u32 s23, s23, 0x100
	s_addc_u32 s24, s24, 0
	s_add_u32 s14, s14, 0x100
	s_addc_u32 s15, s15, 0
	s_cmp_gt_u32 s27, 13
	s_cbranch_scc0 .LBB0_620
	s_setprio 0
	s_and_b64 vcc, exec, s[6:7]
	s_cbranch_vccz .LBB0_623
	s_barrier

.LBB0_675:
	s_add_i32 s14, s17, -2
	s_add_u32 s15, s10, 0x100
	s_addc_u32 s23, s11, 0
	s_add_u32 s10, s12, 0x80
	v_mov_b32_e32 v4, 0
	s_addc_u32 s11, s13, 0
	s_mov_b32 s12, 0
	s_waitcnt lgkmcnt(0)
	s_waitcnt lgkmcnt(0)
	v_mov_b64_e32 v[4:5], 0
	v_mov_b64_e32 v[6:7], 0
	v_mov_b64_e32 v[8:9], 0
	v_mov_b64_e32 v[10:11], 0
	v_mov_b64_e32 v[12:13], 0
	v_mov_b64_e32 v[14:15], 0
	v_mov_b64_e32 v[16:17], 0
	v_mov_b64_e32 v[18:19], 0
	v_mov_b64_e32 v[20:21], 0
	v_mov_b64_e32 v[22:23], 0
	v_mov_b64_e32 v[24:25], 0
	v_mov_b64_e32 v[26:27], 0
	v_mov_b64_e32 v[28:29], 0
	v_mov_b64_e32 v[30:31], 0
	v_mov_b64_e32 v[32:33], 0
	v_mov_b64_e32 v[34:35], 0
	v_mov_b64_e32 v[36:37], 0
	v_mov_b64_e32 v[38:39], 0
	v_mov_b64_e32 v[40:41], 0
	v_mov_b64_e32 v[42:43], 0
	v_mov_b64_e32 v[44:45], 0
	v_mov_b64_e32 v[46:47], 0
	v_mov_b64_e32 v[48:49], 0
	v_mov_b64_e32 v[50:51], 0
	v_mov_b64_e32 v[52:53], 0
	v_mov_b64_e32 v[54:55], 0
	v_mov_b64_e32 v[56:57], 0
	v_mov_b64_e32 v[58:59], 0
	v_mov_b64_e32 v[60:61], 0
	v_mov_b64_e32 v[62:63], 0
	v_mov_b64_e32 v[64:65], 0
	v_mov_b64_e32 v[66:67], 0
	v_mov_b64_e32 v[68:69], 0
	v_mov_b64_e32 v[70:71], 0
	v_mov_b64_e32 v[72:73], 0
	v_mov_b64_e32 v[74:75], 0
	v_mov_b64_e32 v[76:77], 0
	v_mov_b64_e32 v[78:79], 0
	v_mov_b64_e32 v[80:81], 0
	v_mov_b64_e32 v[82:83], 0
	v_mov_b64_e32 v[84:85], 0
	v_mov_b64_e32 v[86:87], 0
	v_mov_b64_e32 v[88:89], 0
	v_mov_b64_e32 v[90:91], 0
	v_mov_b64_e32 v[92:93], 0
	v_mov_b64_e32 v[94:95], 0
	v_mov_b64_e32 v[96:97], 0
	v_mov_b64_e32 v[98:99], 0
	v_mov_b64_e32 v[100:101], 0
	v_mov_b64_e32 v[102:103], 0
	v_mov_b64_e32 v[104:105], 0
	v_mov_b64_e32 v[106:107], 0
	v_mov_b64_e32 v[108:109], 0
	v_mov_b64_e32 v[110:111], 0
	v_mov_b64_e32 v[112:113], 0
	v_mov_b64_e32 v[114:115], 0
	v_mov_b64_e32 v[116:117], 0
	v_mov_b64_e32 v[118:119], 0
	v_mov_b64_e32 v[120:121], 0
	v_mov_b64_e32 v[122:123], 0
	v_mov_b64_e32 v[124:125], 0
	v_mov_b64_e32 v[126:127], 0
	v_mov_b64_e32 v[140:141], 0
	v_mov_b64_e32 v[142:143], 0
	v_readfirstlane_b32 s35, v176
	s_nop 3
	s_lshr_b32 s35, s35, 6
	s_cmp_ge_u32 s35, 4
	s_cbranch_scc0 .Lsp_done_3
	s_setprio 1
.Lsp_done_3:
.LBB0_676:
	s_add_i32 s24, s12, 2
	s_add_u32 s27, s10, 0x80
	s_addc_u32 s13, s11, 0
	s_add_i32 s31, 0, 0x10000
	s_cmp_eq_u32 s14, s12
	s_cselect_b32 s13, s1, s13
	s_cselect_b32 s12, s0, s27
	s_cselect_b32 s37, s49, s23
	s_cselect_b32 s36, s48, s15
	s_add_i32 s27, 0, 0x14000
	v_add_u32_e32 v144, s31, v170
	v_add_u32_e32 v152, s27, v170
	ds_read_b128 v[128:131], v144
	ds_read_b128 v[132:135], v144 offset:1024
	ds_read_b128 v[136:139], v144 offset:2048
	ds_read_b128 v[144:147], v144 offset:3072
	ds_read_b128 v[164:167], v152
	ds_read_b128 v[190:193], v152 offset:1024
	ds_read_b128 v[194:197], v152 offset:2048
	ds_read_b128 v[198:201], v152 offset:3072
	v_lshl_add_u64 v[152:153], s[10:11], 0, v[162:163]
	s_add_i32 m0, s51, 0xc000
	ds_read_b128 v[202:205], v172
	ds_read_b128 v[206:209], v172 offset:1024
	ds_read_b128 v[210:213], v172 offset:2048
	ds_read_b128 v[214:217], v172 offset:3072
	ds_read_b128 v[218:221], v172 offset:4096
	ds_read_b128 v[222:225], v172 offset:5120
	ds_read_b128 v[226:229], v172 offset:6144
	ds_read_b128 v[230:233], v172 offset:7168
	global_load_lds_dwordx4 v[152:153], off
	v_lshl_add_u64 v[152:153], s[10:11], 0, v[160:161]
	s_add_i32 m0, s51, 0xe000
	s_nop 0
	global_load_lds_dwordx4 v[152:153], off
	s_waitcnt vmcnt(8)
	s_waitcnt lgkmcnt(0)
	s_barrier
	s_waitcnt lgkmcnt(0)
	v_mfma_f32_16x16x32_bf16 v[140:143], v[128:131], v[202:205], v[140:143]
	v_mfma_f32_16x16x32_bf16 v[124:127], v[136:139], v[202:205], v[124:127]
	v_mfma_f32_16x16x32_bf16 v[112:115], v[128:131], v[210:213], v[112:115]
	v_mfma_f32_16x16x32_bf16 v[108:111], v[136:139], v[210:213], v[108:111]
	v_mfma_f32_16x16x32_bf16 v[96:99], v[128:131], v[218:221], v[96:99]
	v_mfma_f32_16x16x32_bf16 v[92:95], v[136:139], v[218:221], v[92:95]
	v_mfma_f32_16x16x32_bf16 v[80:83], v[128:131], v[226:229], v[80:83]
	v_mfma_f32_16x16x32_bf16 v[76:79], v[136:139], v[226:229], v[76:79]
	v_mfma_f32_16x16x32_bf16 v[140:143], v[132:135], v[206:209], v[140:143]
	v_mfma_f32_16x16x32_bf16 v[124:127], v[144:147], v[206:209], v[124:127]
	v_mfma_f32_16x16x32_bf16 v[112:115], v[132:135], v[214:217], v[112:115]
	v_mfma_f32_16x16x32_bf16 v[108:111], v[144:147], v[214:217], v[108:111]
	v_mfma_f32_16x16x32_bf16 v[96:99], v[132:135], v[222:225], v[96:99]
	v_mfma_f32_16x16x32_bf16 v[92:95], v[144:147], v[222:225], v[92:95]
	v_mfma_f32_16x16x32_bf16 v[80:83], v[132:135], v[230:233], v[80:83]
	v_mfma_f32_16x16x32_bf16 v[76:79], v[144:147], v[230:233], v[76:79]
	v_mfma_f32_16x16x32_bf16 v[120:123], v[164:167], v[202:205], v[120:123]
	v_mfma_f32_16x16x32_bf16 v[116:119], v[194:197], v[202:205], v[116:119]
	v_mfma_f32_16x16x32_bf16 v[104:107], v[164:167], v[210:213], v[104:107]
	v_mfma_f32_16x16x32_bf16 v[100:103], v[194:197], v[210:213], v[100:103]
	v_mfma_f32_16x16x32_bf16 v[88:91], v[164:167], v[218:221], v[88:91]
	v_mfma_f32_16x16x32_bf16 v[84:87], v[194:197], v[218:221], v[84:87]
	v_mfma_f32_16x16x32_bf16 v[72:75], v[164:167], v[226:229], v[72:75]
	v_mfma_f32_16x16x32_bf16 v[68:71], v[194:197], v[226:229], v[68:71]
	v_mfma_f32_16x16x32_bf16 v[120:123], v[190:193], v[206:209], v[120:123]
	v_mfma_f32_16x16x32_bf16 v[116:119], v[198:201], v[206:209], v[116:119]
	v_mfma_f32_16x16x32_bf16 v[104:107], v[190:193], v[214:217], v[104:107]
	v_mfma_f32_16x16x32_bf16 v[100:103], v[198:201], v[214:217], v[100:103]
	v_mfma_f32_16x16x32_bf16 v[88:91], v[190:193], v[222:225], v[88:91]
	v_mfma_f32_16x16x32_bf16 v[84:87], v[198:201], v[222:225], v[84:87]
	v_mfma_f32_16x16x32_bf16 v[72:75], v[190:193], v[230:233], v[72:75]
	v_mfma_f32_16x16x32_bf16 v[68:71], v[198:201], v[230:233], v[68:71]
	s_barrier
	s_add_i32 s31, s31, s19
	v_lshl_add_u64 v[152:153], s[36:37], 0, v[0:1]
	s_mov_b32 m0, s31
	ds_read_b128 v[202:205], v172 offset:16384
	ds_read_b128 v[206:209], v172 offset:17408
	ds_read_b128 v[210:213], v172 offset:18432
	ds_read_b128 v[214:217], v172 offset:19456
	ds_read_b128 v[218:221], v172 offset:20480
	ds_read_b128 v[222:225], v172 offset:21504
	ds_read_b128 v[226:229], v172 offset:22528
	ds_read_b128 v[230:233], v172 offset:23552
	global_load_lds_dwordx4 v[152:153], off
	s_add_i32 m0, s31, 0x2000
	v_lshl_add_u64 v[168:169], s[36:37], 0, v[158:159]
	s_add_u32 s36, s36, s88
	s_addc_u32 s37, s37, 0
	s_add_i32 s27, s27, s19
	global_load_lds_dwordx4 v[168:169], off
	v_lshl_add_u64 v[174:175], s[36:37], 0, v[0:1]
	s_mov_b32 m0, s27
	v_lshl_add_u64 v[234:235], s[36:37], 0, v[158:159]
	global_load_lds_dwordx4 v[174:175], off
	s_add_i32 m0, s27, 0x2000
	v_lshl_add_u64 v[236:237], s[12:13], 0, v[0:1]
	global_load_lds_dwordx4 v[234:235], off
	s_mov_b32 m0, s51
	v_lshl_add_u64 v[238:239], s[12:13], 0, v[158:159]
	global_load_lds_dwordx4 v[236:237], off
	s_mov_b32 m0, s52
	s_nop 0
	global_load_lds_dwordx4 v[238:239], off
	s_waitcnt vmcnt(8)
	s_waitcnt lgkmcnt(0)
	s_barrier
	s_waitcnt lgkmcnt(0)
	v_mfma_f32_16x16x32_bf16 v[64:67], v[128:131], v[202:205], v[64:67]
	v_mfma_f32_16x16x32_bf16 v[60:63], v[136:139], v[202:205], v[60:63]
	v_mfma_f32_16x16x32_bf16 v[48:51], v[128:131], v[210:213], v[48:51]
	v_mfma_f32_16x16x32_bf16 v[44:47], v[136:139], v[210:213], v[44:47]
	v_mfma_f32_16x16x32_bf16 v[32:35], v[128:131], v[218:221], v[32:35]
	v_mfma_f32_16x16x32_bf16 v[28:31], v[136:139], v[218:221], v[28:31]
	v_mfma_f32_16x16x32_bf16 v[16:19], v[128:131], v[226:229], v[16:19]
	v_mfma_f32_16x16x32_bf16 v[12:15], v[136:139], v[226:229], v[12:15]
	v_mfma_f32_16x16x32_bf16 v[64:67], v[132:135], v[206:209], v[64:67]
	v_mfma_f32_16x16x32_bf16 v[60:63], v[144:147], v[206:209], v[60:63]
	v_mfma_f32_16x16x32_bf16 v[48:51], v[132:135], v[214:217], v[48:51]
	v_mfma_f32_16x16x32_bf16 v[44:47], v[144:147], v[214:217], v[44:47]
	v_mfma_f32_16x16x32_bf16 v[32:35], v[132:135], v[222:225], v[32:35]
	v_mfma_f32_16x16x32_bf16 v[28:31], v[144:147], v[222:225], v[28:31]
	v_mfma_f32_16x16x32_bf16 v[16:19], v[132:135], v[230:233], v[16:19]
	v_mfma_f32_16x16x32_bf16 v[12:15], v[144:147], v[230:233], v[12:15]
	v_mfma_f32_16x16x32_bf16 v[56:59], v[164:167], v[202:205], v[56:59]
	v_mfma_f32_16x16x32_bf16 v[52:55], v[194:197], v[202:205], v[52:55]
	v_mfma_f32_16x16x32_bf16 v[40:43], v[164:167], v[210:213], v[40:43]
	v_mfma_f32_16x16x32_bf16 v[36:39], v[194:197], v[210:213], v[36:39]
	v_mfma_f32_16x16x32_bf16 v[24:27], v[164:167], v[218:221], v[24:27]
	v_mfma_f32_16x16x32_bf16 v[20:23], v[194:197], v[218:221], v[20:23]
	v_mfma_f32_16x16x32_bf16 v[8:11], v[164:167], v[226:229], v[8:11]
	v_mfma_f32_16x16x32_bf16 v[4:7], v[194:197], v[226:229], v[4:7]
	v_mfma_f32_16x16x32_bf16 v[56:59], v[190:193], v[206:209], v[56:59]
	v_mfma_f32_16x16x32_bf16 v[52:55], v[198:201], v[206:209], v[52:55]
	v_mfma_f32_16x16x32_bf16 v[40:43], v[190:193], v[214:217], v[40:43]
	v_mfma_f32_16x16x32_bf16 v[36:39], v[198:201], v[214:217], v[36:39]
	v_mfma_f32_16x16x32_bf16 v[24:27], v[190:193], v[222:225], v[24:27]
	v_mfma_f32_16x16x32_bf16 v[20:23], v[198:201], v[222:225], v[20:23]
	v_mfma_f32_16x16x32_bf16 v[8:11], v[190:193], v[230:233], v[8:11]
	v_mfma_f32_16x16x32_bf16 v[4:7], v[198:201], v[230:233], v[4:7]
	s_barrier
	s_add_i32 s27, 0, 0x18000
	s_add_i32 s31, 0, 0x1c000
	v_add_u32_e32 v144, s27, v170
	v_add_u32_e32 v173, s31, v170
	ds_read_b128 v[128:131], v144
	ds_read_b128 v[132:135], v144 offset:1024
	ds_read_b128 v[136:139], v144 offset:2048
	ds_read_b128 v[144:147], v144 offset:3072
	ds_read_b128 v[164:167], v173
	ds_read_b128 v[190:193], v173 offset:1024
	ds_read_b128 v[194:197], v173 offset:2048
	ds_read_b128 v[198:201], v173 offset:3072
	s_add_u32 s12, s12, s88
	s_addc_u32 s13, s13, 0
	s_mov_b32 m0, s53
	v_lshl_add_u64 v[240:241], s[12:13], 0, v[0:1]
	ds_read_b128 v[202:205], v172 offset:32768
	ds_read_b128 v[206:209], v172 offset:33792
	ds_read_b128 v[210:213], v172 offset:34816
	ds_read_b128 v[214:217], v172 offset:35840
	ds_read_b128 v[218:221], v172 offset:36864
	ds_read_b128 v[222:225], v172 offset:37888
	ds_read_b128 v[226:229], v172 offset:38912
	ds_read_b128 v[230:233], v172 offset:39936
	global_load_lds_dwordx4 v[240:241], off
	v_lshl_add_u64 v[240:241], s[12:13], 0, v[158:159]
	s_mov_b32 m0, s54
	s_nop 0
	global_load_lds_dwordx4 v[240:241], off
	s_waitcnt vmcnt(8)
	s_waitcnt lgkmcnt(0)
	s_barrier
	s_waitcnt lgkmcnt(0)
	v_mfma_f32_16x16x32_bf16 v[140:143], v[128:131], v[202:205], v[140:143]
	v_mfma_f32_16x16x32_bf16 v[124:127], v[136:139], v[202:205], v[124:127]
	v_mfma_f32_16x16x32_bf16 v[112:115], v[128:131], v[210:213], v[112:115]
	v_mfma_f32_16x16x32_bf16 v[108:111], v[136:139], v[210:213], v[108:111]
	v_mfma_f32_16x16x32_bf16 v[96:99], v[128:131], v[218:221], v[96:99]
	v_mfma_f32_16x16x32_bf16 v[92:95], v[136:139], v[218:221], v[92:95]
	v_mfma_f32_16x16x32_bf16 v[80:83], v[128:131], v[226:229], v[80:83]
	v_mfma_f32_16x16x32_bf16 v[76:79], v[136:139], v[226:229], v[76:79]
	v_mfma_f32_16x16x32_bf16 v[140:143], v[132:135], v[206:209], v[140:143]
	v_mfma_f32_16x16x32_bf16 v[124:127], v[144:147], v[206:209], v[124:127]
	v_mfma_f32_16x16x32_bf16 v[112:115], v[132:135], v[214:217], v[112:115]
	v_mfma_f32_16x16x32_bf16 v[108:111], v[144:147], v[214:217], v[108:111]
	v_mfma_f32_16x16x32_bf16 v[96:99], v[132:135], v[222:225], v[96:99]
	v_mfma_f32_16x16x32_bf16 v[92:95], v[144:147], v[222:225], v[92:95]
	v_mfma_f32_16x16x32_bf16 v[80:83], v[132:135], v[230:233], v[80:83]
	v_mfma_f32_16x16x32_bf16 v[76:79], v[144:147], v[230:233], v[76:79]
	v_mfma_f32_16x16x32_bf16 v[120:123], v[164:167], v[202:205], v[120:123]
	v_mfma_f32_16x16x32_bf16 v[116:119], v[194:197], v[202:205], v[116:119]
	v_mfma_f32_16x16x32_bf16 v[104:107], v[164:167], v[210:213], v[104:107]
	v_mfma_f32_16x16x32_bf16 v[100:103], v[194:197], v[210:213], v[100:103]
	v_mfma_f32_16x16x32_bf16 v[88:91], v[164:167], v[218:221], v[88:91]
	v_mfma_f32_16x16x32_bf16 v[84:87], v[194:197], v[218:221], v[84:87]
	v_mfma_f32_16x16x32_bf16 v[72:75], v[164:167], v[226:229], v[72:75]
	v_mfma_f32_16x16x32_bf16 v[68:71], v[194:197], v[226:229], v[68:71]
	v_mfma_f32_16x16x32_bf16 v[120:123], v[190:193], v[206:209], v[120:123]
	v_mfma_f32_16x16x32_bf16 v[116:119], v[198:201], v[206:209], v[116:119]
	v_mfma_f32_16x16x32_bf16 v[104:107], v[190:193], v[214:217], v[104:107]
	v_mfma_f32_16x16x32_bf16 v[100:103], v[198:201], v[214:217], v[100:103]
	v_mfma_f32_16x16x32_bf16 v[88:91], v[190:193], v[222:225], v[88:91]
	v_mfma_f32_16x16x32_bf16 v[84:87], v[198:201], v[222:225], v[84:87]
	v_mfma_f32_16x16x32_bf16 v[72:75], v[190:193], v[230:233], v[72:75]
	v_mfma_f32_16x16x32_bf16 v[68:71], v[198:201], v[230:233], v[68:71]
	s_barrier
	s_add_i32 s12, s27, s19
	v_lshl_add_u64 v[152:153], v[152:153], 0, s[84:85]
	s_mov_b32 m0, s12
	ds_read_b128 v[202:205], v172 offset:49152
	ds_read_b128 v[206:209], v172 offset:50176
	ds_read_b128 v[210:213], v172 offset:51200
	ds_read_b128 v[214:217], v172 offset:52224
	ds_read_b128 v[218:221], v172 offset:53248
	ds_read_b128 v[222:225], v172 offset:54272
	ds_read_b128 v[226:229], v172 offset:55296
	ds_read_b128 v[230:233], v172 offset:56320
	global_load_lds_dwordx4 v[152:153], off
	v_lshl_add_u64 v[152:153], v[168:169], 0, s[84:85]
	s_add_i32 m0, s12, 0x2000
	s_add_i32 s12, s31, s19
	global_load_lds_dwordx4 v[152:153], off
	v_lshl_add_u64 v[152:153], v[174:175], 0, s[84:85]
	s_mov_b32 m0, s12
	s_nop 0
	global_load_lds_dwordx4 v[152:153], off
	v_lshl_add_u64 v[152:153], v[234:235], 0, s[84:85]
	s_add_i32 m0, s12, 0x2000
	s_nop 0
	global_load_lds_dwordx4 v[152:153], off
	v_lshl_add_u64 v[152:153], v[236:237], 0, s[84:85]
	s_mov_b32 m0, s55
	s_nop 0
	global_load_lds_dwordx4 v[152:153], off
	v_lshl_add_u64 v[152:153], v[238:239], 0, s[84:85]
	s_mov_b32 m0, s58
	s_nop 0
	global_load_lds_dwordx4 v[152:153], off
	s_waitcnt vmcnt(8)
	s_waitcnt lgkmcnt(0)
	s_barrier
	s_waitcnt lgkmcnt(0)
	v_mfma_f32_16x16x32_bf16 v[64:67], v[128:131], v[202:205], v[64:67]
	v_mfma_f32_16x16x32_bf16 v[60:63], v[136:139], v[202:205], v[60:63]
	v_mfma_f32_16x16x32_bf16 v[48:51], v[128:131], v[210:213], v[48:51]
	v_mfma_f32_16x16x32_bf16 v[44:47], v[136:139], v[210:213], v[44:47]
	v_mfma_f32_16x16x32_bf16 v[32:35], v[128:131], v[218:221], v[32:35]
	v_mfma_f32_16x16x32_bf16 v[28:31], v[136:139], v[218:221], v[28:31]
	v_mfma_f32_16x16x32_bf16 v[16:19], v[128:131], v[226:229], v[16:19]
	v_mfma_f32_16x16x32_bf16 v[12:15], v[136:139], v[226:229], v[12:15]
	v_mfma_f32_16x16x32_bf16 v[64:67], v[132:135], v[206:209], v[64:67]
	v_mfma_f32_16x16x32_bf16 v[60:63], v[144:147], v[206:209], v[60:63]
	v_mfma_f32_16x16x32_bf16 v[48:51], v[132:135], v[214:217], v[48:51]
	v_mfma_f32_16x16x32_bf16 v[44:47], v[144:147], v[214:217], v[44:47]
	v_mfma_f32_16x16x32_bf16 v[32:35], v[132:135], v[222:225], v[32:35]
	v_mfma_f32_16x16x32_bf16 v[28:31], v[144:147], v[222:225], v[28:31]
	v_mfma_f32_16x16x32_bf16 v[16:19], v[132:135], v[230:233], v[16:19]
	v_mfma_f32_16x16x32_bf16 v[12:15], v[144:147], v[230:233], v[12:15]
	v_mfma_f32_16x16x32_bf16 v[56:59], v[164:167], v[202:205], v[56:59]
	v_mfma_f32_16x16x32_bf16 v[52:55], v[194:197], v[202:205], v[52:55]
	v_mfma_f32_16x16x32_bf16 v[40:43], v[164:167], v[210:213], v[40:43]
	v_mfma_f32_16x16x32_bf16 v[36:39], v[194:197], v[210:213], v[36:39]
	v_mfma_f32_16x16x32_bf16 v[24:27], v[164:167], v[218:221], v[24:27]
	v_mfma_f32_16x16x32_bf16 v[20:23], v[194:197], v[218:221], v[20:23]
	v_mfma_f32_16x16x32_bf16 v[8:11], v[164:167], v[226:229], v[8:11]
	v_mfma_f32_16x16x32_bf16 v[4:7], v[194:197], v[226:229], v[4:7]
	v_mfma_f32_16x16x32_bf16 v[56:59], v[190:193], v[206:209], v[56:59]
	v_mfma_f32_16x16x32_bf16 v[52:55], v[198:201], v[206:209], v[52:55]
	v_mfma_f32_16x16x32_bf16 v[40:43], v[190:193], v[214:217], v[40:43]
	v_mfma_f32_16x16x32_bf16 v[36:39], v[198:201], v[214:217], v[36:39]
	v_mfma_f32_16x16x32_bf16 v[24:27], v[190:193], v[222:225], v[24:27]
	v_mfma_f32_16x16x32_bf16 v[20:23], v[198:201], v[222:225], v[20:23]
	v_mfma_f32_16x16x32_bf16 v[8:11], v[190:193], v[230:233], v[8:11]
	v_mfma_f32_16x16x32_bf16 v[4:7], v[198:201], v[230:233], v[4:7]
	s_barrier
	s_add_u32 s15, s15, 0x100
	s_addc_u32 s23, s23, 0
	s_add_u32 s10, s10, 0x100
	s_addc_u32 s11, s11, 0
	s_cmp_ge_i32 s24, s17
	s_mov_b32 s12, s24
	s_cbranch_scc0 .LBB0_676
	s_setprio 0
	s_and_b64 vcc, exec, s[46:47]
	s_cbranch_vccz .LBB0_679
	s_barrier

.LBB0_765:
	s_ashr_i32 s59, s58, 31
	s_lshl_b64 s[16:17], s[58:59], 19
	s_add_u32 s18, s88, s16
	s_addc_u32 s19, s79, s17
	s_and_b64 s[16:17], s[54:55], exec
	s_cselect_b32 s59, s19, s11
	s_cselect_b32 s74, s18, s10
	s_ashr_i32 s9, s8, 31
	s_lshl_b64 s[16:17], s[8:9], 19
	v_readlane_b32 s0, v252, 47
	v_readlane_b32 s1, v252, 48
	s_add_u32 s16, s0, s16
	s_addc_u32 s17, s1, s17
	s_and_b64 vcc, s[54:55], exec
	s_cselect_b32 s9, s17, s13
	s_cselect_b32 s23, s16, s12
	s_add_u32 s24, s12, 0x100
	s_addc_u32 s27, s13, 0
	s_add_u32 vcc_lo, s10, 0x40080
	v_mov_b32_e32 v4, 0
	s_addc_u32 vcc_hi, s11, 0
	s_mov_b32 s77, -2
	v_mov_b64_e32 v[4:5], 0
	v_mov_b64_e32 v[6:7], 0
	v_mov_b64_e32 v[8:9], 0
	v_mov_b64_e32 v[10:11], 0
	v_mov_b64_e32 v[12:13], 0
	v_mov_b64_e32 v[14:15], 0
	v_mov_b64_e32 v[16:17], 0
	v_mov_b64_e32 v[18:19], 0
	v_mov_b64_e32 v[20:21], 0
	v_mov_b64_e32 v[22:23], 0
	v_mov_b64_e32 v[24:25], 0
	v_mov_b64_e32 v[26:27], 0
	v_mov_b64_e32 v[28:29], 0
	v_mov_b64_e32 v[30:31], 0
	v_mov_b64_e32 v[32:33], 0
	v_mov_b64_e32 v[34:35], 0
	v_mov_b64_e32 v[36:37], 0
	v_mov_b64_e32 v[38:39], 0
	v_mov_b64_e32 v[40:41], 0
	v_mov_b64_e32 v[42:43], 0
	v_mov_b64_e32 v[44:45], 0
	v_mov_b64_e32 v[46:47], 0
	v_mov_b64_e32 v[48:49], 0
	v_mov_b64_e32 v[50:51], 0
	v_mov_b64_e32 v[52:53], 0
	v_mov_b64_e32 v[54:55], 0
	v_mov_b64_e32 v[56:57], 0
	v_mov_b64_e32 v[58:59], 0
	v_mov_b64_e32 v[60:61], 0
	v_mov_b64_e32 v[62:63], 0
	v_mov_b64_e32 v[64:65], 0
	v_mov_b64_e32 v[66:67], 0
	v_mov_b64_e32 v[68:69], 0
	v_mov_b64_e32 v[70:71], 0
	v_mov_b64_e32 v[72:73], 0
	v_mov_b64_e32 v[74:75], 0
	v_mov_b64_e32 v[76:77], 0
	v_mov_b64_e32 v[78:79], 0
	v_mov_b64_e32 v[80:81], 0
	v_mov_b64_e32 v[82:83], 0
	v_mov_b64_e32 v[84:85], 0
	v_mov_b64_e32 v[86:87], 0
	v_mov_b64_e32 v[88:89], 0
	v_mov_b64_e32 v[90:91], 0
	v_mov_b64_e32 v[92:93], 0
	v_mov_b64_e32 v[94:95], 0
	v_mov_b64_e32 v[96:97], 0
	v_mov_b64_e32 v[98:99], 0
	v_mov_b64_e32 v[100:101], 0
	v_mov_b64_e32 v[102:103], 0
	v_mov_b64_e32 v[104:105], 0
	v_mov_b64_e32 v[106:107], 0
	v_mov_b64_e32 v[108:109], 0
	v_mov_b64_e32 v[110:111], 0
	v_mov_b64_e32 v[112:113], 0
	v_mov_b64_e32 v[114:115], 0
	v_mov_b64_e32 v[116:117], 0
	v_mov_b64_e32 v[118:119], 0
	v_mov_b64_e32 v[120:121], 0
	v_mov_b64_e32 v[122:123], 0
	v_mov_b64_e32 v[124:125], 0
	v_mov_b64_e32 v[126:127], 0
	v_mov_b64_e32 v[128:129], 0
	v_mov_b64_e32 v[130:131], 0
	v_readfirstlane_b32 s35, v176
	s_nop 3
	s_lshr_b32 s35, s35, 6
	s_cmp_ge_u32 s35, 4
	s_cbranch_scc0 .Lsp_done_4
	s_setprio 1
.Lsp_done_4:
.LBB0_766:
	s_add_u32 s10, vcc_lo, 0xfffc0080
	s_addc_u32 s11, vcc_hi, -1
	s_add_i32 s36, 0, 0x10000
	s_cmp_eq_u32 s77, 12
	s_cselect_b32 s13, s59, s11
	s_cselect_b32 s12, s74, s10
	v_add_u32_e32 v152, s36, v3
	s_cselect_b32 s11, s9, s27
	s_cselect_b32 s10, s23, s24
	s_add_i32 s0, 0, 0x14000
	ds_read_b128 v[168:171], v152
	ds_read_b128 v[172:175], v152 offset:1024
	ds_read_b128 v[190:193], v152 offset:2048
	ds_read_b128 v[194:197], v152 offset:3072
	v_add_u32_e32 v152, s0, v3
	ds_read_b128 v[198:201], v152
	ds_read_b128 v[202:205], v152 offset:1024
	ds_read_b128 v[206:209], v152 offset:2048
	ds_read_b128 v[210:213], v152 offset:3072
	v_lshl_add_u64 v[164:165], vcc, 0, v[162:163]
	s_add_i32 m0, s15, 0xc000
	ds_read_b128 v[214:217], v167
	ds_read_b128 v[218:221], v167 offset:1024
	ds_read_b128 v[222:225], v167 offset:2048
	ds_read_b128 v[226:229], v167 offset:3072
	ds_read_b128 v[230:233], v167 offset:4096
	ds_read_b128 v[234:237], v167 offset:5120
	ds_read_b128 v[238:241], v167 offset:6144
	ds_read_b128 v[242:245], v167 offset:7168
	global_load_lds_dwordx4 v[164:165], off
	v_lshl_add_u64 v[164:165], vcc, 0, v[160:161]
	s_add_i32 m0, s15, 0xe000
	s_nop 0
	global_load_lds_dwordx4 v[164:165], off
	s_waitcnt vmcnt(8)
	s_waitcnt lgkmcnt(0)
	s_barrier
	s_waitcnt lgkmcnt(0)
	v_mfma_f32_16x16x32_bf16 v[128:131], v[168:171], v[214:217], v[128:131]
	v_mfma_f32_16x16x32_bf16 v[124:127], v[190:193], v[214:217], v[124:127]
	v_mfma_f32_16x16x32_bf16 v[116:119], v[168:171], v[222:225], v[116:119]
	v_mfma_f32_16x16x32_bf16 v[108:111], v[190:193], v[222:225], v[108:111]
	v_mfma_f32_16x16x32_bf16 v[100:103], v[168:171], v[230:233], v[100:103]
	v_mfma_f32_16x16x32_bf16 v[92:95], v[190:193], v[230:233], v[92:95]
	v_mfma_f32_16x16x32_bf16 v[84:87], v[168:171], v[238:241], v[84:87]
	v_mfma_f32_16x16x32_bf16 v[76:79], v[190:193], v[238:241], v[76:79]
	v_mfma_f32_16x16x32_bf16 v[128:131], v[172:175], v[218:221], v[128:131]
	v_mfma_f32_16x16x32_bf16 v[124:127], v[194:197], v[218:221], v[124:127]
	v_mfma_f32_16x16x32_bf16 v[116:119], v[172:175], v[226:229], v[116:119]
	v_mfma_f32_16x16x32_bf16 v[108:111], v[194:197], v[226:229], v[108:111]
	v_mfma_f32_16x16x32_bf16 v[100:103], v[172:175], v[234:237], v[100:103]
	v_mfma_f32_16x16x32_bf16 v[92:95], v[194:197], v[234:237], v[92:95]
	v_mfma_f32_16x16x32_bf16 v[84:87], v[172:175], v[242:245], v[84:87]
	v_mfma_f32_16x16x32_bf16 v[76:79], v[194:197], v[242:245], v[76:79]
	v_mfma_f32_16x16x32_bf16 v[120:123], v[198:201], v[214:217], v[120:123]
	v_mfma_f32_16x16x32_bf16 v[112:115], v[206:209], v[214:217], v[112:115]
	v_mfma_f32_16x16x32_bf16 v[104:107], v[198:201], v[222:225], v[104:107]
	v_mfma_f32_16x16x32_bf16 v[96:99], v[206:209], v[222:225], v[96:99]
	v_mfma_f32_16x16x32_bf16 v[88:91], v[198:201], v[230:233], v[88:91]
	v_mfma_f32_16x16x32_bf16 v[80:83], v[206:209], v[230:233], v[80:83]
	v_mfma_f32_16x16x32_bf16 v[72:75], v[198:201], v[238:241], v[72:75]
	v_mfma_f32_16x16x32_bf16 v[68:71], v[206:209], v[238:241], v[68:71]
	v_mfma_f32_16x16x32_bf16 v[120:123], v[202:205], v[218:221], v[120:123]
	v_mfma_f32_16x16x32_bf16 v[112:115], v[210:213], v[218:221], v[112:115]
	v_mfma_f32_16x16x32_bf16 v[104:107], v[202:205], v[226:229], v[104:107]
	v_mfma_f32_16x16x32_bf16 v[96:99], v[210:213], v[226:229], v[96:99]
	v_mfma_f32_16x16x32_bf16 v[88:91], v[202:205], v[234:237], v[88:91]
	v_mfma_f32_16x16x32_bf16 v[80:83], v[210:213], v[234:237], v[80:83]
	v_mfma_f32_16x16x32_bf16 v[72:75], v[202:205], v[242:245], v[72:75]
	v_mfma_f32_16x16x32_bf16 v[68:71], v[210:213], v[242:245], v[68:71]
	s_barrier
	s_add_i32 s1, s36, s90
	v_lshl_add_u64 v[164:165], s[10:11], 0, v[0:1]
	s_mov_b32 m0, s1
	ds_read_b128 v[214:217], v167 offset:16384
	ds_read_b128 v[218:221], v167 offset:17408
	ds_read_b128 v[222:225], v167 offset:18432
	ds_read_b128 v[226:229], v167 offset:19456
	ds_read_b128 v[230:233], v167 offset:20480
	ds_read_b128 v[234:237], v167 offset:21504
	ds_read_b128 v[238:241], v167 offset:22528
	ds_read_b128 v[242:245], v167 offset:23552
	global_load_lds_dwordx4 v[164:165], off
	s_add_i32 m0, s1, 0x2000
	s_add_u32 s36, s10, 0x40000
	v_lshl_add_u64 v[246:247], s[10:11], 0, v[132:133]
	s_addc_u32 s37, s11, 0
	s_add_i32 s0, s0, s90
	global_load_lds_dwordx4 v[246:247], off
	v_lshl_add_u64 v[248:249], s[36:37], 0, v[0:1]
	s_mov_b32 m0, s0
	v_lshl_add_u64 v[250:251], s[12:13], 0, v[132:133]
	global_load_lds_dwordx4 v[248:249], off
	v_lshl_add_u64 v[248:249], s[36:37], 0, v[132:133]
	s_add_i32 m0, s0, 0x2000
	s_nop 0
	global_load_lds_dwordx4 v[248:249], off
	v_lshl_add_u64 v[248:249], s[12:13], 0, v[0:1]
	s_mov_b32 m0, s15
	s_nop 0
	global_load_lds_dwordx4 v[248:249], off
	s_mov_b32 m0, s91
	s_nop 0
	global_load_lds_dwordx4 v[250:251], off
	s_waitcnt vmcnt(8)
	s_waitcnt lgkmcnt(0)
	s_barrier
	s_waitcnt lgkmcnt(0)
	v_mfma_f32_16x16x32_bf16 v[64:67], v[168:171], v[214:217], v[64:67]
	v_mfma_f32_16x16x32_bf16 v[60:63], v[190:193], v[214:217], v[60:63]
	v_mfma_f32_16x16x32_bf16 v[52:55], v[168:171], v[222:225], v[52:55]
	v_mfma_f32_16x16x32_bf16 v[44:47], v[190:193], v[222:225], v[44:47]
	v_mfma_f32_16x16x32_bf16 v[36:39], v[168:171], v[230:233], v[36:39]
	v_mfma_f32_16x16x32_bf16 v[28:31], v[190:193], v[230:233], v[28:31]
	v_mfma_f32_16x16x32_bf16 v[20:23], v[168:171], v[238:241], v[20:23]
	v_mfma_f32_16x16x32_bf16 v[12:15], v[190:193], v[238:241], v[12:15]
	v_mfma_f32_16x16x32_bf16 v[64:67], v[172:175], v[218:221], v[64:67]
	v_mfma_f32_16x16x32_bf16 v[60:63], v[194:197], v[218:221], v[60:63]
	v_mfma_f32_16x16x32_bf16 v[52:55], v[172:175], v[226:229], v[52:55]
	v_mfma_f32_16x16x32_bf16 v[44:47], v[194:197], v[226:229], v[44:47]
	v_mfma_f32_16x16x32_bf16 v[36:39], v[172:175], v[234:237], v[36:39]
	v_mfma_f32_16x16x32_bf16 v[28:31], v[194:197], v[234:237], v[28:31]
	v_mfma_f32_16x16x32_bf16 v[20:23], v[172:175], v[242:245], v[20:23]
	v_mfma_f32_16x16x32_bf16 v[12:15], v[194:197], v[242:245], v[12:15]
	v_mfma_f32_16x16x32_bf16 v[56:59], v[198:201], v[214:217], v[56:59]
	v_mfma_f32_16x16x32_bf16 v[48:51], v[206:209], v[214:217], v[48:51]
	v_mfma_f32_16x16x32_bf16 v[40:43], v[198:201], v[222:225], v[40:43]
	v_mfma_f32_16x16x32_bf16 v[32:35], v[206:209], v[222:225], v[32:35]
	v_mfma_f32_16x16x32_bf16 v[24:27], v[198:201], v[230:233], v[24:27]
	v_mfma_f32_16x16x32_bf16 v[16:19], v[206:209], v[230:233], v[16:19]
	v_mfma_f32_16x16x32_bf16 v[8:11], v[198:201], v[238:241], v[8:11]
	v_mfma_f32_16x16x32_bf16 v[4:7], v[206:209], v[238:241], v[4:7]
	v_mfma_f32_16x16x32_bf16 v[56:59], v[202:205], v[218:221], v[56:59]
	v_mfma_f32_16x16x32_bf16 v[48:51], v[210:213], v[218:221], v[48:51]
	v_mfma_f32_16x16x32_bf16 v[40:43], v[202:205], v[226:229], v[40:43]
	v_mfma_f32_16x16x32_bf16 v[32:35], v[210:213], v[226:229], v[32:35]
	v_mfma_f32_16x16x32_bf16 v[24:27], v[202:205], v[234:237], v[24:27]
	v_mfma_f32_16x16x32_bf16 v[16:19], v[210:213], v[234:237], v[16:19]
	v_mfma_f32_16x16x32_bf16 v[8:11], v[202:205], v[242:245], v[8:11]
	v_mfma_f32_16x16x32_bf16 v[4:7], v[210:213], v[242:245], v[4:7]
	s_barrier
	s_add_i32 s0, 0, 0x18000
	v_add_u32_e32 v152, s0, v3
	s_add_i32 s1, 0, 0x1c000
	ds_read_b128 v[168:171], v152
	ds_read_b128 v[172:175], v152 offset:1024
	ds_read_b128 v[190:193], v152 offset:2048
	ds_read_b128 v[194:197], v152 offset:3072
	v_add_u32_e32 v152, s1, v3
	ds_read_b128 v[198:201], v152
	ds_read_b128 v[202:205], v152 offset:1024
	ds_read_b128 v[206:209], v152 offset:2048
	ds_read_b128 v[210:213], v152 offset:3072
	s_add_u32 s12, s12, 0x40000
	s_addc_u32 s13, s13, 0
	s_mov_b32 m0, s31
	v_lshl_add_u64 v[152:153], s[12:13], 0, v[0:1]
	ds_read_b128 v[214:217], v167 offset:32768
	ds_read_b128 v[218:221], v167 offset:33792
	ds_read_b128 v[222:225], v167 offset:34816
	ds_read_b128 v[226:229], v167 offset:35840
	ds_read_b128 v[230:233], v167 offset:36864
	ds_read_b128 v[234:237], v167 offset:37888
	ds_read_b128 v[238:241], v167 offset:38912
	ds_read_b128 v[242:245], v167 offset:39936
	global_load_lds_dwordx4 v[152:153], off
	v_lshl_add_u64 v[152:153], s[12:13], 0, v[132:133]
	s_mov_b32 m0, s22
	s_nop 0
	global_load_lds_dwordx4 v[152:153], off
	s_waitcnt vmcnt(8)
	s_waitcnt lgkmcnt(0)
	s_barrier
	s_waitcnt lgkmcnt(0)
	v_mfma_f32_16x16x32_bf16 v[128:131], v[168:171], v[214:217], v[128:131]
	v_mfma_f32_16x16x32_bf16 v[124:127], v[190:193], v[214:217], v[124:127]
	v_mfma_f32_16x16x32_bf16 v[116:119], v[168:171], v[222:225], v[116:119]
	v_mfma_f32_16x16x32_bf16 v[108:111], v[190:193], v[222:225], v[108:111]
	v_mfma_f32_16x16x32_bf16 v[100:103], v[168:171], v[230:233], v[100:103]
	v_mfma_f32_16x16x32_bf16 v[92:95], v[190:193], v[230:233], v[92:95]
	v_mfma_f32_16x16x32_bf16 v[84:87], v[168:171], v[238:241], v[84:87]
	v_mfma_f32_16x16x32_bf16 v[76:79], v[190:193], v[238:241], v[76:79]
	v_mfma_f32_16x16x32_bf16 v[128:131], v[172:175], v[218:221], v[128:131]
	v_mfma_f32_16x16x32_bf16 v[124:127], v[194:197], v[218:221], v[124:127]
	v_mfma_f32_16x16x32_bf16 v[116:119], v[172:175], v[226:229], v[116:119]
	v_mfma_f32_16x16x32_bf16 v[108:111], v[194:197], v[226:229], v[108:111]
	v_mfma_f32_16x16x32_bf16 v[100:103], v[172:175], v[234:237], v[100:103]
	v_mfma_f32_16x16x32_bf16 v[92:95], v[194:197], v[234:237], v[92:95]
	v_mfma_f32_16x16x32_bf16 v[84:87], v[172:175], v[242:245], v[84:87]
	v_mfma_f32_16x16x32_bf16 v[76:79], v[194:197], v[242:245], v[76:79]
	v_mfma_f32_16x16x32_bf16 v[120:123], v[198:201], v[214:217], v[120:123]
	v_mfma_f32_16x16x32_bf16 v[112:115], v[206:209], v[214:217], v[112:115]
	v_mfma_f32_16x16x32_bf16 v[104:107], v[198:201], v[222:225], v[104:107]
	v_mfma_f32_16x16x32_bf16 v[96:99], v[206:209], v[222:225], v[96:99]
	v_mfma_f32_16x16x32_bf16 v[88:91], v[198:201], v[230:233], v[88:91]
	v_mfma_f32_16x16x32_bf16 v[80:83], v[206:209], v[230:233], v[80:83]
	v_mfma_f32_16x16x32_bf16 v[72:75], v[198:201], v[238:241], v[72:75]
	v_mfma_f32_16x16x32_bf16 v[68:71], v[206:209], v[238:241], v[68:71]
	v_mfma_f32_16x16x32_bf16 v[120:123], v[202:205], v[218:221], v[120:123]
	v_mfma_f32_16x16x32_bf16 v[112:115], v[210:213], v[218:221], v[112:115]
	v_mfma_f32_16x16x32_bf16 v[104:107], v[202:205], v[226:229], v[104:107]
	v_mfma_f32_16x16x32_bf16 v[96:99], v[210:213], v[226:229], v[96:99]
	v_mfma_f32_16x16x32_bf16 v[88:91], v[202:205], v[234:237], v[88:91]
	v_mfma_f32_16x16x32_bf16 v[80:83], v[210:213], v[234:237], v[80:83]
	v_mfma_f32_16x16x32_bf16 v[72:75], v[202:205], v[242:245], v[72:75]
	v_mfma_f32_16x16x32_bf16 v[68:71], v[210:213], v[242:245], v[68:71]
	s_barrier
	s_add_i32 s0, s0, s90
	v_lshl_add_u64 v[152:153], v[164:165], 0, s[84:85]
	s_mov_b32 m0, s0
	ds_read_b128 v[214:217], v167 offset:49152
	ds_read_b128 v[218:221], v167 offset:50176
	ds_read_b128 v[222:225], v167 offset:51200
	ds_read_b128 v[226:229], v167 offset:52224
	ds_read_b128 v[230:233], v167 offset:53248
	ds_read_b128 v[234:237], v167 offset:54272
	ds_read_b128 v[238:241], v167 offset:55296
	ds_read_b128 v[242:245], v167 offset:56320
	global_load_lds_dwordx4 v[152:153], off
	s_add_i32 m0, s0, 0x2000
	s_add_u32 s10, s10, 0x40080
	v_lshl_add_u64 v[152:153], v[246:247], 0, s[84:85]
	s_addc_u32 s11, s11, 0
	s_add_i32 s0, s1, s90
	global_load_lds_dwordx4 v[152:153], off
	v_lshl_add_u64 v[152:153], s[10:11], 0, v[0:1]
	s_mov_b32 m0, s0
	s_nop 0
	global_load_lds_dwordx4 v[152:153], off
	v_lshl_add_u64 v[152:153], s[10:11], 0, v[132:133]
	s_add_i32 m0, s0, 0x2000
	s_nop 0
	global_load_lds_dwordx4 v[152:153], off
	v_lshl_add_u64 v[152:153], v[248:249], 0, s[84:85]
	s_mov_b32 m0, s94
	s_nop 0
	global_load_lds_dwordx4 v[152:153], off
	v_lshl_add_u64 v[152:153], v[250:251], 0, s[84:85]
	s_mov_b32 m0, s70
	s_nop 0
	global_load_lds_dwordx4 v[152:153], off
	s_waitcnt vmcnt(8)
	s_waitcnt lgkmcnt(0)
	s_barrier
	s_waitcnt lgkmcnt(0)
	v_mfma_f32_16x16x32_bf16 v[64:67], v[168:171], v[214:217], v[64:67]
	v_mfma_f32_16x16x32_bf16 v[60:63], v[190:193], v[214:217], v[60:63]
	v_mfma_f32_16x16x32_bf16 v[52:55], v[168:171], v[222:225], v[52:55]
	v_mfma_f32_16x16x32_bf16 v[44:47], v[190:193], v[222:225], v[44:47]
	v_mfma_f32_16x16x32_bf16 v[36:39], v[168:171], v[230:233], v[36:39]
	v_mfma_f32_16x16x32_bf16 v[28:31], v[190:193], v[230:233], v[28:31]
	v_mfma_f32_16x16x32_bf16 v[20:23], v[168:171], v[238:241], v[20:23]
	v_mfma_f32_16x16x32_bf16 v[12:15], v[190:193], v[238:241], v[12:15]
	v_mfma_f32_16x16x32_bf16 v[64:67], v[172:175], v[218:221], v[64:67]
	v_mfma_f32_16x16x32_bf16 v[60:63], v[194:197], v[218:221], v[60:63]
	v_mfma_f32_16x16x32_bf16 v[52:55], v[172:175], v[226:229], v[52:55]
	v_mfma_f32_16x16x32_bf16 v[44:47], v[194:197], v[226:229], v[44:47]
	v_mfma_f32_16x16x32_bf16 v[36:39], v[172:175], v[234:237], v[36:39]
	v_mfma_f32_16x16x32_bf16 v[28:31], v[194:197], v[234:237], v[28:31]
	v_mfma_f32_16x16x32_bf16 v[20:23], v[172:175], v[242:245], v[20:23]
	v_mfma_f32_16x16x32_bf16 v[12:15], v[194:197], v[242:245], v[12:15]
	v_mfma_f32_16x16x32_bf16 v[56:59], v[198:201], v[214:217], v[56:59]
	v_mfma_f32_16x16x32_bf16 v[48:51], v[206:209], v[214:217], v[48:51]
	v_mfma_f32_16x16x32_bf16 v[40:43], v[198:201], v[222:225], v[40:43]
	v_mfma_f32_16x16x32_bf16 v[32:35], v[206:209], v[222:225], v[32:35]
	v_mfma_f32_16x16x32_bf16 v[24:27], v[198:201], v[230:233], v[24:27]
	v_mfma_f32_16x16x32_bf16 v[16:19], v[206:209], v[230:233], v[16:19]
	v_mfma_f32_16x16x32_bf16 v[8:11], v[198:201], v[238:241], v[8:11]
	v_mfma_f32_16x16x32_bf16 v[4:7], v[206:209], v[238:241], v[4:7]
	v_mfma_f32_16x16x32_bf16 v[56:59], v[202:205], v[218:221], v[56:59]
	v_mfma_f32_16x16x32_bf16 v[48:51], v[210:213], v[218:221], v[48:51]
	v_mfma_f32_16x16x32_bf16 v[40:43], v[202:205], v[226:229], v[40:43]
	v_mfma_f32_16x16x32_bf16 v[32:35], v[210:213], v[226:229], v[32:35]
	v_mfma_f32_16x16x32_bf16 v[24:27], v[202:205], v[234:237], v[24:27]
	v_mfma_f32_16x16x32_bf16 v[16:19], v[210:213], v[234:237], v[16:19]
	v_mfma_f32_16x16x32_bf16 v[8:11], v[202:205], v[242:245], v[8:11]
	v_mfma_f32_16x16x32_bf16 v[4:7], v[210:213], v[242:245], v[4:7]
	s_barrier
	s_add_i32 s77, s77, 2
	s_add_u32 s24, s24, 0x100
	s_addc_u32 s27, s27, 0
	s_add_u32 vcc_lo, vcc_lo, 0x100
	s_addc_u32 vcc_hi, vcc_hi, 0
	s_cmp_gt_u32 s77, 13
	s_cbranch_scc0 .LBB0_766
	s_setprio 0
	s_and_b64 vcc, exec, s[6:7]
	s_cbranch_vccz .LBB0_777
	s_barrier
	v_lshl_or_b32 v164, s14, 8, v166
	v_ashrrev_i32_e32 v165, 31, v164
	v_lshlrev_b64 v[190:191], 2, v[164:165]
	v_lshl_add_u64 v[190:191], s[2:3], 0, v[190:191]
	global_load_dwordx4 v[192:195], v[190:191], off
	global_load_dwordx4 v[196:199], v[190:191], off offset:64
	global_load_dwordx4 v[200:203], v[190:191], off offset:512
	global_load_dwordx4 v[204:207], v[190:191], off offset:576
	s_waitcnt vmcnt(0)
	s_and_saveexec_b64 s[10:11], s[38:39]
	s_cbranch_execnz .LBB0_778
